# write-through sc1 policy on the big epilogue stores (ACT, residual stream) so the grid barrier L2 write-back is short; + nt on streamed-once P1 loads; MLA loop role-split
# speedup vs baseline: 1.0081x; 1.0056x over previous
; __device__ __forceinline__ unsigned cvt_pk_bf16(float lo, float hi) { f32x2c_t v = {lo, hi}; bf16x2c_t b = __builtin_convertvector(v, bf16x2c_t); return __builtin_bit_cast(unsigned, b); }
; __device__ __forceinline__ unsigned swi2(float a0, float a1, float b0, float b1) {
;     const f32x2s a = {a0, a1}, b = {b0, b1};
;     f32x2s e; e.x = __builtin_amdgcn_exp2f(-a.x); e.y = __builtin_amdgcn_exp2f(-a.y);
;     const f32x2s d = e + 1.0f; f32x2s r; r.x = __builtin_amdgcn_rcpf(d.x); r.y = __builtin_amdgcn_rcpf(d.y);
;     const f32x2s o = (a * b) * r;
;     return cvt_pk_bf16(o.x, o.y);
; }
;     __device__ __forceinline__ void operator()(const f32x4 (&acc)[2][2][4][2], const Unit& u, int wr, int wc, int fr, int fq) const {
;     ...
;         for (int ai = 0; ai < 2; ++ai)
; #pragma unroll
;             for (int m = 0; m < 4; ++m) {
;                 bf16_t* rowp = O + (size_t)(row0 + ai * HALF + m * 16) * 2816 + col0;
;                 const f32x4 a0 = acc[ai][0][m][0], a1 = acc[ai][0][m][1], b0 = acc[ai][1][m][0], b1 = acc[ai][1][m][1];
;                 u32x4 w;
;                 w.x = swi2(a0[0], a0[1], b0[0], b0[1]); w.y = swi2(a0[2], a0[3], b0[2], b0[3]);
;                 w.z = swi2(a1[0], a1[1], b1[0], b1[1]); w.w = swi2(a1[2], a1[3], b1[2], b1[3]);
.LBB0_279:
	v_exp_f32_e64 v158, -v126
	v_exp_f32_e64 v159, -v127
	v_exp_f32_e64 v154, -v124
	v_exp_f32_e64 v155, -v125
	v_pk_mul_f32 v[120:121], v[124:125], v[120:121]
	v_pk_add_f32 v[124:125], v[158:159], 1.0 op_sel_hi:[1,0]
	v_pk_mul_f32 v[122:123], v[126:127], v[122:123]
	v_rcp_f32_e32 v124, v124
	v_rcp_f32_e32 v125, v125
	v_pk_add_f32 v[154:155], v[154:155], 1.0 op_sel_hi:[1,0]
	v_exp_f32_e64 v126, -v116
	v_rcp_f32_e32 v154, v154
	v_rcp_f32_e32 v155, v155
	v_exp_f32_e64 v127, -v117
	v_pk_mul_f32 v[122:123], v[124:125], v[122:123]
	v_exp_f32_e64 v124, -v118
	v_exp_f32_e64 v125, -v119
	v_pk_mul_f32 v[120:121], v[154:155], v[120:121]
	v_pk_mul_f32 v[114:115], v[118:119], v[114:115]
	v_cvt_pk_bf16_f32 v120, v120, v121
	v_cvt_pk_bf16_f32 v121, v122, v123
	v_pk_add_f32 v[122:123], v[126:127], 1.0 op_sel_hi:[1,0]
	v_pk_add_f32 v[118:119], v[124:125], 1.0 op_sel_hi:[1,0]
	v_rcp_f32_e32 v122, v122
	v_rcp_f32_e32 v123, v123
	v_rcp_f32_e32 v118, v118
	v_rcp_f32_e32 v119, v119
	v_pk_mul_f32 v[112:113], v[116:117], v[112:113]
	v_exp_f32_e64 v116, -v110
	v_pk_mul_f32 v[112:113], v[122:123], v[112:113]
	v_exp_f32_e64 v117, -v111
	v_cvt_pk_bf16_f32 v122, v112, v113
	v_pk_mul_f32 v[112:113], v[118:119], v[114:115]
	v_pk_mul_f32 v[104:105], v[108:109], v[104:105]
	v_cvt_pk_bf16_f32 v123, v112, v113
	v_exp_f32_e64 v112, -v108
	v_exp_f32_e64 v113, -v109
	v_pk_add_f32 v[108:109], v[116:117], 1.0 op_sel_hi:[1,0]
	v_pk_mul_f32 v[106:107], v[110:111], v[106:107]
	v_rcp_f32_e32 v108, v108
	v_rcp_f32_e32 v109, v109
	v_pk_add_f32 v[112:113], v[112:113], 1.0 op_sel_hi:[1,0]
	v_exp_f32_e64 v110, -v100
	v_rcp_f32_e32 v112, v112
	v_rcp_f32_e32 v113, v113
	v_exp_f32_e64 v111, -v101
	v_pk_mul_f32 v[106:107], v[108:109], v[106:107]
	v_exp_f32_e64 v108, -v102
	v_exp_f32_e64 v109, -v103
	v_pk_mul_f32 v[104:105], v[112:113], v[104:105]
	v_pk_mul_f32 v[98:99], v[102:103], v[98:99]
	v_cvt_pk_bf16_f32 v104, v104, v105
	v_cvt_pk_bf16_f32 v105, v106, v107
	v_pk_add_f32 v[106:107], v[110:111], 1.0 op_sel_hi:[1,0]
	v_pk_add_f32 v[102:103], v[108:109], 1.0 op_sel_hi:[1,0]
	v_rcp_f32_e32 v106, v106
	v_rcp_f32_e32 v107, v107
	v_rcp_f32_e32 v102, v102
	v_rcp_f32_e32 v103, v103
	v_pk_mul_f32 v[96:97], v[100:101], v[96:97]
	v_exp_f32_e64 v100, -v94
	v_pk_mul_f32 v[96:97], v[106:107], v[96:97]
	v_exp_f32_e64 v101, -v95
	v_cvt_pk_bf16_f32 v106, v96, v97
	v_pk_mul_f32 v[96:97], v[102:103], v[98:99]
	v_pk_mul_f32 v[88:89], v[92:93], v[88:89]
	v_cvt_pk_bf16_f32 v107, v96, v97
	v_exp_f32_e64 v96, -v92
	v_exp_f32_e64 v97, -v93
	v_pk_add_f32 v[92:93], v[100:101], 1.0 op_sel_hi:[1,0]
	v_pk_mul_f32 v[90:91], v[94:95], v[90:91]
	v_rcp_f32_e32 v92, v92
	v_rcp_f32_e32 v93, v93
	v_pk_add_f32 v[96:97], v[96:97], 1.0 op_sel_hi:[1,0]
	v_exp_f32_e64 v94, -v84
	v_rcp_f32_e32 v96, v96
	v_rcp_f32_e32 v97, v97
	v_exp_f32_e64 v95, -v85
	v_pk_mul_f32 v[90:91], v[92:93], v[90:91]
	v_exp_f32_e64 v92, -v86
	v_exp_f32_e64 v93, -v87
	v_pk_mul_f32 v[88:89], v[96:97], v[88:89]
	v_pk_mul_f32 v[82:83], v[86:87], v[82:83]
	v_cvt_pk_bf16_f32 v88, v88, v89
	v_cvt_pk_bf16_f32 v89, v90, v91
	v_pk_add_f32 v[90:91], v[94:95], 1.0 op_sel_hi:[1,0]
	v_pk_add_f32 v[86:87], v[92:93], 1.0 op_sel_hi:[1,0]
	v_rcp_f32_e32 v90, v90
	v_rcp_f32_e32 v91, v91
	v_rcp_f32_e32 v86, v86
	v_rcp_f32_e32 v87, v87
	v_pk_mul_f32 v[80:81], v[84:85], v[80:81]
	v_exp_f32_e64 v84, -v78
	v_pk_mul_f32 v[80:81], v[90:91], v[80:81]
	v_exp_f32_e64 v85, -v79
	v_cvt_pk_bf16_f32 v90, v80, v81
	v_pk_mul_f32 v[80:81], v[86:87], v[82:83]
	v_pk_mul_f32 v[72:73], v[76:77], v[72:73]
	v_cvt_pk_bf16_f32 v91, v80, v81
	v_exp_f32_e64 v80, -v76
	v_exp_f32_e64 v81, -v77
	v_pk_add_f32 v[76:77], v[84:85], 1.0 op_sel_hi:[1,0]
	v_pk_mul_f32 v[74:75], v[78:79], v[74:75]
	v_rcp_f32_e32 v76, v76
	v_rcp_f32_e32 v77, v77
	v_pk_add_f32 v[80:81], v[80:81], 1.0 op_sel_hi:[1,0]
	v_exp_f32_e64 v78, -v68
	v_rcp_f32_e32 v80, v80
	v_rcp_f32_e32 v81, v81
	v_exp_f32_e64 v79, -v69
	v_pk_mul_f32 v[74:75], v[76:77], v[74:75]
	v_exp_f32_e64 v76, -v70
	v_exp_f32_e64 v77, -v71
	v_pk_mul_f32 v[72:73], v[80:81], v[72:73]
	v_pk_mul_f32 v[66:67], v[70:71], v[66:67]
	v_cvt_pk_bf16_f32 v72, v72, v73
	v_cvt_pk_bf16_f32 v73, v74, v75
	v_pk_add_f32 v[74:75], v[78:79], 1.0 op_sel_hi:[1,0]
	v_pk_add_f32 v[70:71], v[76:77], 1.0 op_sel_hi:[1,0]
	v_rcp_f32_e32 v74, v74
	v_rcp_f32_e32 v75, v75
	v_rcp_f32_e32 v70, v70
	v_rcp_f32_e32 v71, v71
	v_pk_mul_f32 v[64:65], v[68:69], v[64:65]
	v_exp_f32_e64 v68, -v62
	v_pk_mul_f32 v[64:65], v[74:75], v[64:65]
	v_exp_f32_e64 v69, -v63
	v_cvt_pk_bf16_f32 v74, v64, v65
	v_pk_mul_f32 v[64:65], v[70:71], v[66:67]
	v_pk_mul_f32 v[56:57], v[60:61], v[56:57]
	v_cvt_pk_bf16_f32 v75, v64, v65
	v_exp_f32_e64 v64, -v60
	v_exp_f32_e64 v65, -v61
	v_pk_add_f32 v[60:61], v[68:69], 1.0 op_sel_hi:[1,0]
	v_pk_mul_f32 v[58:59], v[62:63], v[58:59]
	v_rcp_f32_e32 v60, v60
	v_rcp_f32_e32 v61, v61
	v_pk_add_f32 v[64:65], v[64:65], 1.0 op_sel_hi:[1,0]
	v_exp_f32_e64 v62, -v52
	v_rcp_f32_e32 v64, v64
	v_rcp_f32_e32 v65, v65
	v_exp_f32_e64 v63, -v53
	v_pk_mul_f32 v[58:59], v[60:61], v[58:59]
	v_exp_f32_e64 v60, -v54
	v_exp_f32_e64 v61, -v55
	v_pk_mul_f32 v[56:57], v[64:65], v[56:57]
	v_pk_mul_f32 v[50:51], v[54:55], v[50:51]
	v_cvt_pk_bf16_f32 v56, v56, v57
; __device__ __forceinline__ unsigned cvt_pk_bf16(float lo, float hi) { f32x2c_t v = {lo, hi}; bf16x2c_t b = __builtin_convertvector(v, bf16x2c_t); return __builtin_bit_cast(unsigned, b); }
; __device__ __forceinline__ unsigned swi2(float a0, float a1, float b0, float b1) {
;     const f32x2s a = {a0, a1}, b = {b0, b1};
;     f32x2s e; e.x = __builtin_amdgcn_exp2f(-a.x); e.y = __builtin_amdgcn_exp2f(-a.y);
;     const f32x2s d = e + 1.0f; f32x2s r; r.x = __builtin_amdgcn_rcpf(d.x); r.y = __builtin_amdgcn_rcpf(d.y);
;     const f32x2s o = (a * b) * r;
;     return cvt_pk_bf16(o.x, o.y);
;     __device__ __forceinline__ void operator()(const f32x4 (&acc)[2][2][4][2], const Unit& u, int wr, int wc, int fr, int fq) const {
;     ...
;         const int row0 = u.pm * BM + wr * 64 + fr, col0 = u.pn * 128 + wc * 32 + 8 * fq;
; #pragma unroll
;         for (int ai = 0; ai < 2; ++ai)
; #pragma unroll
;             for (int m = 0; m < 4; ++m) {
;                 bf16_t* rowp = O + (size_t)(row0 + ai * HALF + m * 16) * 2816 + col0;
;                 const f32x4 a0 = acc[ai][0][m][0], a1 = acc[ai][0][m][1], b0 = acc[ai][1][m][0], b1 = acc[ai][1][m][1];
;                 u32x4 w;
;                 w.x = swi2(a0[0], a0[1], b0[0], b0[1]); w.y = swi2(a0[2], a0[3], b0[2], b0[3]);
;                 w.z = swi2(a1[0], a1[1], b1[0], b1[1]); w.w = swi2(a1[2], a1[3], b1[2], b1[3]);
;                 *(u32x4*)rowp = w;
	v_cvt_pk_bf16_f32 v57, v58, v59
	v_pk_add_f32 v[58:59], v[62:63], 1.0 op_sel_hi:[1,0]
	v_pk_add_f32 v[54:55], v[60:61], 1.0 op_sel_hi:[1,0]
	v_rcp_f32_e32 v58, v58
	v_rcp_f32_e32 v59, v59
	v_rcp_f32_e32 v54, v54
	v_rcp_f32_e32 v55, v55
	v_pk_mul_f32 v[48:49], v[52:53], v[48:49]
	v_exp_f32_e64 v52, -v46
	v_pk_mul_f32 v[48:49], v[58:59], v[48:49]
	v_exp_f32_e64 v53, -v47
	v_cvt_pk_bf16_f32 v58, v48, v49
	v_pk_mul_f32 v[48:49], v[54:55], v[50:51]
	v_pk_mul_f32 v[40:41], v[44:45], v[40:41]
	v_cvt_pk_bf16_f32 v59, v48, v49
	v_exp_f32_e64 v48, -v44
	v_exp_f32_e64 v49, -v45
	v_pk_add_f32 v[44:45], v[52:53], 1.0 op_sel_hi:[1,0]
	v_pk_mul_f32 v[42:43], v[46:47], v[42:43]
	v_rcp_f32_e32 v44, v44
	v_rcp_f32_e32 v45, v45
	v_pk_add_f32 v[48:49], v[48:49], 1.0 op_sel_hi:[1,0]
	v_exp_f32_e64 v46, -v36
	v_rcp_f32_e32 v48, v48
	v_rcp_f32_e32 v49, v49
	v_exp_f32_e64 v47, -v37
	v_pk_mul_f32 v[42:43], v[44:45], v[42:43]
	v_exp_f32_e64 v44, -v38
	v_exp_f32_e64 v45, -v39
	v_pk_mul_f32 v[40:41], v[48:49], v[40:41]
	v_pk_mul_f32 v[34:35], v[38:39], v[34:35]
	v_cvt_pk_bf16_f32 v40, v40, v41
	v_cvt_pk_bf16_f32 v41, v42, v43
	v_pk_add_f32 v[42:43], v[46:47], 1.0 op_sel_hi:[1,0]
	v_pk_add_f32 v[38:39], v[44:45], 1.0 op_sel_hi:[1,0]
	v_rcp_f32_e32 v42, v42
	v_rcp_f32_e32 v43, v43
	v_rcp_f32_e32 v38, v38
	v_rcp_f32_e32 v39, v39
	v_pk_mul_f32 v[32:33], v[36:37], v[32:33]
	v_exp_f32_e64 v36, -v30
	v_pk_mul_f32 v[32:33], v[42:43], v[32:33]
	v_exp_f32_e64 v37, -v31
	v_cvt_pk_bf16_f32 v42, v32, v33
	v_pk_mul_f32 v[32:33], v[38:39], v[34:35]
	v_pk_mul_f32 v[24:25], v[28:29], v[24:25]
	v_cvt_pk_bf16_f32 v43, v32, v33
	v_exp_f32_e64 v32, -v28
	v_exp_f32_e64 v33, -v29
	v_pk_add_f32 v[28:29], v[36:37], 1.0 op_sel_hi:[1,0]
	v_pk_mul_f32 v[26:27], v[30:31], v[26:27]
	v_rcp_f32_e32 v28, v28
	v_rcp_f32_e32 v29, v29
	v_pk_add_f32 v[32:33], v[32:33], 1.0 op_sel_hi:[1,0]
	v_exp_f32_e64 v30, -v20
	v_rcp_f32_e32 v32, v32
	v_rcp_f32_e32 v33, v33
	v_exp_f32_e64 v31, -v21
	v_pk_mul_f32 v[26:27], v[28:29], v[26:27]
	v_exp_f32_e64 v28, -v22
	v_exp_f32_e64 v29, -v23
	v_pk_mul_f32 v[24:25], v[32:33], v[24:25]
	v_pk_mul_f32 v[18:19], v[22:23], v[18:19]
	v_cvt_pk_bf16_f32 v24, v24, v25
	v_cvt_pk_bf16_f32 v25, v26, v27
	v_pk_add_f32 v[26:27], v[30:31], 1.0 op_sel_hi:[1,0]
	v_pk_add_f32 v[22:23], v[28:29], 1.0 op_sel_hi:[1,0]
	v_rcp_f32_e32 v26, v26
	v_rcp_f32_e32 v27, v27
	v_rcp_f32_e32 v22, v22
	v_rcp_f32_e32 v23, v23
	v_pk_mul_f32 v[16:17], v[20:21], v[16:17]
	v_exp_f32_e64 v20, -v14
	v_pk_mul_f32 v[16:17], v[26:27], v[16:17]
	v_exp_f32_e64 v21, -v15
	v_cvt_pk_bf16_f32 v26, v16, v17
	v_pk_mul_f32 v[16:17], v[22:23], v[18:19]
	v_pk_mul_f32 v[8:9], v[12:13], v[8:9]
	v_cvt_pk_bf16_f32 v27, v16, v17
	v_exp_f32_e64 v16, -v12
	v_exp_f32_e64 v17, -v13
	v_pk_add_f32 v[12:13], v[20:21], 1.0 op_sel_hi:[1,0]
	v_pk_mul_f32 v[10:11], v[14:15], v[10:11]
	v_rcp_f32_e32 v12, v12
	v_rcp_f32_e32 v13, v13
	v_pk_add_f32 v[16:17], v[16:17], 1.0 op_sel_hi:[1,0]
	v_exp_f32_e64 v14, -v4
	v_rcp_f32_e32 v16, v16
	v_rcp_f32_e32 v17, v17
	v_exp_f32_e64 v15, -v5
	v_pk_mul_f32 v[10:11], v[12:13], v[10:11]
	v_exp_f32_e64 v12, -v6
	v_exp_f32_e64 v13, -v7
	v_pk_mul_f32 v[8:9], v[16:17], v[8:9]
	v_pk_mul_f32 v[2:3], v[6:7], v[2:3]
	v_cvt_pk_bf16_f32 v8, v8, v9
	v_cvt_pk_bf16_f32 v9, v10, v11
	v_pk_add_f32 v[10:11], v[14:15], 1.0 op_sel_hi:[1,0]
	v_pk_add_f32 v[6:7], v[12:13], 1.0 op_sel_hi:[1,0]
	v_rcp_f32_e32 v10, v10
	v_rcp_f32_e32 v11, v11
	v_mov_b32_e32 v144, v147
	v_mov_b32_e32 v145, v146
	s_lshl_b32 s19, s62, 7
	v_rcp_f32_e32 v6, v6
	v_rcp_f32_e32 v7, v7
	s_lshl_b32 s17, s40, 8
	s_or_b32 s19, s19, s48
	v_lshl_add_u32 v144, v144, 3, s19
	s_add_i32 s17, s17, s47
	v_pk_mul_f32 v[0:1], v[4:5], v[0:1]
	v_add_u32_e32 v152, s17, v145
	v_ashrrev_i32_e32 v145, 31, v144
	v_pk_mul_f32 v[0:1], v[10:11], v[0:1]
	v_lshl_add_u64 v[144:145], v[144:145], 1, s[22:23]
	v_add_u32_e32 v114, 16, v152
	v_add_u32_e32 v98, 32, v152
	v_add_u32_e32 v82, 48, v152
	v_add_u32_e32 v66, 0x80, v152
	v_add_u32_e32 v50, 0x90, v152
	v_add_u32_e32 v34, 0xa0, v152
	v_add_u32_e32 v18, 0xb0, v152
	v_cvt_pk_bf16_f32 v10, v0, v1
	v_pk_mul_f32 v[0:1], v[6:7], v[2:3]
	v_mad_i64_i32 v[156:157], s[42:43], v152, s61, v[144:145]
	v_mad_i64_i32 v[114:115], s[42:43], v114, s61, v[144:145]
	v_mad_i64_i32 v[98:99], s[42:43], v98, s61, v[144:145]
	v_mad_i64_i32 v[82:83], s[42:43], v82, s61, v[144:145]
	v_mad_i64_i32 v[66:67], s[42:43], v66, s61, v[144:145]
	v_mad_i64_i32 v[50:51], s[42:43], v50, s61, v[144:145]
	v_mad_i64_i32 v[34:35], s[42:43], v34, s61, v[144:145]
	v_mad_i64_i32 v[18:19], s[42:43], v18, s61, v[144:145]
	v_cvt_pk_bf16_f32 v11, v0, v1
	s_andn2_b64 vcc, exec, s[0:1]
	s_mov_b64 s[0:1], -1
	global_store_dwordx4 v[156:157], v[120:123], off sc1
	global_store_dwordx4 v[114:115], v[104:107], off sc1
	global_store_dwordx4 v[98:99], v[88:91], off sc1
	global_store_dwordx4 v[82:83], v[72:75], off sc1
	global_store_dwordx4 v[66:67], v[56:59], off sc1
	global_store_dwordx4 v[50:51], v[40:43], off sc1
	global_store_dwordx4 v[34:35], v[24:27], off sc1
	global_store_dwordx4 v[18:19], v[8:11], off sc1
	s_cbranch_vccnz .LBB0_272
	s_andn2_b64 vcc, exec, s[10:11]
	s_cbranch_vccnz .LBB0_271
	s_barrier
	s_branch .LBB0_271

; __device__ __forceinline__ unsigned cvt_pk_bf16(float lo, float hi) { f32x2c_t v = {lo, hi}; bf16x2c_t b = __builtin_convertvector(v, bf16x2c_t); return __builtin_bit_cast(unsigned, b); }
; __device__ __forceinline__ f32x4 bf4_lo(u32x4 w) { return (f32x4){__uint_as_float(w.x << 16), __uint_as_float(w.x & 0xffff0000u), __uint_as_float(w.y << 16), __uint_as_float(w.y & 0xffff0000u)}; }
;     __device__ __forceinline__ void operator()(const f32x4 (&acc)[2][2][4][2], const Unit& u, int wr, int wc, int fr, int fq) const {
;     ...
;         const int row0 = u.pm * BM + wr * 64 + fr, col0 = u.pn * BM + wc * 32 + 8 * fq, b = u.pm >> 4;
;         f32x4 gv[2][2];
; #pragma unroll
;         for (int bj = 0; bj < 2; ++bj)
; #pragma unroll
;             for (int n = 0; n < 2; ++n) gv[bj][n] = *(const f32x4*)(gate + (size_t)b * NMODC + col0 + bj * HALF + n * 4) * (MIX ? 1.0f : 0.5f);
;         u32x4 xw[2][4][2];
;         if constexpr (!XF32) {
; #pragma unroll
;             for (int ai = 0; ai < 2; ++ai)
; #pragma unroll
;                 for (int m = 0; m < 4; ++m)
; #pragma unroll
;                     for (int bj = 0; bj < 2; ++bj) xw[ai][m][bj] = *(const u32x4*)((const bf16_t*)xin + (size_t)(row0 + ai * HALF + m * 16) * 1024 + col0 + bj * HALF);
;         }
; #pragma unroll
;         for (int ai = 0; ai < 2; ++ai)
; #pragma unroll
;             for (int m = 0; m < 4; ++m) { const int row = row0 + ai * HALF + m * 16; const size_t off = (size_t)row * 1024 + col0; float rs = 1.f; if constexpr (MIX) { const float* sp = rs2 + 4 * row + 2; rs = 1.0f / sqrtf((sp[0] + sp[1]) * (1.f / 512.f) + NEPS); }
; #pragma unroll
;                 for (int bj = 0; bj < 2; ++bj) { f32x4 x0, x1;
;                     if constexpr (XF32) { x0 = *(const f32x4*)((const float*)xin + off + bj * HALF); x1 = *(const f32x4*)((const float*)xin + off + bj * HALF + 4); }
;                     else { const u32x4 w = xw[ai][m][bj]; x0 = bf4_lo(w); x1 = bf4_hi(w); }
;                     const f32x4 o0 = x0 + gv[bj][0] * (acc[ai][bj][m][0] * rs), o1 = x1 + gv[bj][1] * (acc[ai][bj][m][1] * rs);
;                     u32x4 w; w.x = cvt_pk_bf16(o0[0], o0[1]); w.y = cvt_pk_bf16(o0[2], o0[3]); w.z = cvt_pk_bf16(o1[0], o1[1]); w.w = cvt_pk_bf16(o1[2], o1[3]);
;                     *(u32x4*)(xout + off + bj * HALF) = w; } }
.LBB0_359:
	s_lshl_b32 s38, s61, 8
	v_mov_b32_e32 v144, v155
	v_mov_b32_e32 v152, v154
	s_add_i32 s40, s38, s47
	s_lshl_b32 s38, s62, 8
	s_or_b32 s38, s38, s48
	v_lshl_add_u32 v144, v144, 3, s38
	s_ashr_i32 s38, s61, 4
	s_mul_hi_i32 s39, s38, 0x9000
	s_mul_i32 s38, s38, 0x9000
	s_add_u32 s38, s37, s38
	s_addc_u32 s39, s46, s39
	v_ashrrev_i32_e32 v145, 31, v144
	v_add_u32_e32 v152, s40, v152
	v_lshl_add_u64 v[150:151], v[144:145], 2, s[38:39]
	v_ashrrev_i32_e32 v153, 31, v152
	global_load_dwordx4 v[160:163], v[150:151], off offset:16
	global_load_dwordx4 v[146:149], v[150:151], off
	v_lshlrev_b64 v[152:153], 10, v[152:153]
	v_lshl_add_u64 v[152:153], v[152:153], 0, v[144:145]
	v_lshl_add_u64 v[180:181], v[152:153], 2, s[52:53]
	global_load_dwordx4 v[164:167], v[180:181], off
	global_load_dwordx4 v[168:171], v[180:181], off offset:16
	global_load_dwordx4 v[172:175], v[150:151], off offset:528
	global_load_dwordx4 v[176:179], v[150:151], off offset:512
	v_lshl_add_u64 v[182:183], v[152:153], 1, s[24:25]
	s_mov_b64 s[38:39], 0x4000
	s_and_b64 vcc, exec, s[0:1]
	s_mov_b64 s[0:1], -1
	s_waitcnt vmcnt(0)
	v_pk_mul_f32 v[150:151], v[160:161], 0.5 op_sel_hi:[1,0]
	v_pk_mul_f32 v[144:145], v[148:149], 0.5 op_sel_hi:[1,0]
	v_pk_mul_f32 v[146:147], v[146:147], 0.5 op_sel_hi:[1,0]
	v_pk_mul_f32 v[148:149], v[162:163], 0.5 op_sel_hi:[1,0]
	v_pk_fma_f32 v[126:127], v[126:127], v[144:145], v[166:167]
	v_pk_fma_f32 v[124:125], v[124:125], v[146:147], v[164:165]
	v_pk_fma_f32 v[160:161], v[122:123], v[148:149], v[170:171]
	v_pk_fma_f32 v[122:123], v[120:121], v[150:151], v[168:169]
	v_cvt_pk_bf16_f32 v120, v124, v125
	v_cvt_pk_bf16_f32 v121, v126, v127
	v_cvt_pk_bf16_f32 v122, v122, v123
	v_cvt_pk_bf16_f32 v123, v160, v161
	global_store_dwordx4 v[182:183], v[120:123], off sc1
	global_load_dwordx4 v[160:163], v[180:181], off offset:512
	global_load_dwordx4 v[164:167], v[180:181], off offset:528
	v_pk_mul_f32 v[120:121], v[178:179], 0.5 op_sel_hi:[1,0]
	v_pk_mul_f32 v[122:123], v[176:177], 0.5 op_sel_hi:[1,0]
	v_pk_mul_f32 v[124:125], v[174:175], 0.5 op_sel_hi:[1,0]
	v_pk_mul_f32 v[126:127], v[172:173], 0.5 op_sel_hi:[1,0]
	v_lshl_add_u64 v[168:169], v[152:153], 0, s[38:39]
	v_lshl_add_u64 v[170:171], v[168:169], 2, s[52:53]
	s_mov_b64 s[38:39], 0x8000
	s_waitcnt vmcnt(1)
	v_pk_fma_f32 v[118:119], v[118:119], v[120:121], v[162:163]
	v_pk_fma_f32 v[116:117], v[116:117], v[122:123], v[160:161]
	s_waitcnt vmcnt(0)
	v_pk_fma_f32 v[160:161], v[114:115], v[124:125], v[166:167]
	v_pk_fma_f32 v[114:115], v[112:113], v[126:127], v[164:165]
	v_cvt_pk_bf16_f32 v112, v116, v117
	v_cvt_pk_bf16_f32 v113, v118, v119
	v_cvt_pk_bf16_f32 v114, v114, v115
	v_cvt_pk_bf16_f32 v115, v160, v161
	global_store_dwordx4 v[182:183], v[112:115], off offset:256 sc1
	global_load_dwordx4 v[112:115], v[170:171], off
	s_nop 0
	global_load_dwordx4 v[116:119], v[170:171], off offset:16
	v_lshl_add_u64 v[160:161], v[168:169], 1, s[24:25]
	s_waitcnt vmcnt(1)
	v_pk_fma_f32 v[110:111], v[110:111], v[144:145], v[114:115]
	v_pk_fma_f32 v[108:109], v[108:109], v[146:147], v[112:113]
	s_waitcnt vmcnt(0)
	v_pk_fma_f32 v[112:113], v[106:107], v[148:149], v[118:119]
	v_pk_fma_f32 v[106:107], v[104:105], v[150:151], v[116:117]
	v_cvt_pk_bf16_f32 v104, v108, v109
	v_cvt_pk_bf16_f32 v105, v110, v111
	v_cvt_pk_bf16_f32 v106, v106, v107
	v_cvt_pk_bf16_f32 v107, v112, v113
	global_store_dwordx4 v[160:161], v[104:107], off sc1
	global_load_dwordx4 v[104:107], v[170:171], off offset:512
	s_nop 0
	global_load_dwordx4 v[108:111], v[170:171], off offset:528
	v_lshl_add_u64 v[112:113], v[152:153], 0, s[38:39]
	v_lshl_add_u64 v[114:115], v[112:113], 2, s[52:53]
	s_mov_b64 s[38:39], 0xc000
	s_waitcnt vmcnt(1)
	v_pk_fma_f32 v[102:103], v[102:103], v[120:121], v[106:107]
	v_pk_fma_f32 v[100:101], v[100:101], v[122:123], v[104:105]
	s_waitcnt vmcnt(0)
	v_pk_fma_f32 v[104:105], v[98:99], v[124:125], v[110:111]
	v_pk_fma_f32 v[98:99], v[96:97], v[126:127], v[108:109]
	v_cvt_pk_bf16_f32 v96, v100, v101
	v_cvt_pk_bf16_f32 v97, v102, v103
	v_cvt_pk_bf16_f32 v98, v98, v99
	v_cvt_pk_bf16_f32 v99, v104, v105
	global_store_dwordx4 v[160:161], v[96:99], off offset:256 sc1
	global_load_dwordx4 v[96:99], v[114:115], off
	s_nop 0
	global_load_dwordx4 v[100:103], v[114:115], off offset:16
	v_lshl_add_u64 v[104:105], v[112:113], 1, s[24:25]
	s_waitcnt vmcnt(1)
	v_pk_fma_f32 v[94:95], v[94:95], v[144:145], v[98:99]
	v_pk_fma_f32 v[92:93], v[92:93], v[146:147], v[96:97]
	s_waitcnt vmcnt(0)
	v_pk_fma_f32 v[96:97], v[90:91], v[148:149], v[102:103]
	v_pk_fma_f32 v[90:91], v[88:89], v[150:151], v[100:101]
	v_cvt_pk_bf16_f32 v88, v92, v93
	v_cvt_pk_bf16_f32 v89, v94, v95
	v_cvt_pk_bf16_f32 v90, v90, v91
	v_cvt_pk_bf16_f32 v91, v96, v97
	global_store_dwordx4 v[104:105], v[88:91], off sc1
	global_load_dwordx4 v[88:91], v[114:115], off offset:512
	s_nop 0
	global_load_dwordx4 v[92:95], v[114:115], off offset:528
	v_lshl_add_u64 v[96:97], v[152:153], 0, s[38:39]
	v_lshl_add_u64 v[98:99], v[96:97], 2, s[52:53]
	s_mov_b64 s[38:39], 0x20000
	s_waitcnt vmcnt(1)
	v_pk_fma_f32 v[86:87], v[86:87], v[120:121], v[90:91]
	v_pk_fma_f32 v[84:85], v[84:85], v[122:123], v[88:89]
	s_waitcnt vmcnt(0)
	v_pk_fma_f32 v[88:89], v[82:83], v[124:125], v[94:95]
	v_pk_fma_f32 v[82:83], v[80:81], v[126:127], v[92:93]
	v_cvt_pk_bf16_f32 v80, v84, v85
	v_cvt_pk_bf16_f32 v81, v86, v87
	v_cvt_pk_bf16_f32 v82, v82, v83
	v_cvt_pk_bf16_f32 v83, v88, v89
	global_store_dwordx4 v[104:105], v[80:83], off offset:256 sc1
	global_load_dwordx4 v[80:83], v[98:99], off
	s_nop 0
	global_load_dwordx4 v[84:87], v[98:99], off offset:16
	v_lshl_add_u64 v[88:89], v[96:97], 1, s[24:25]
	s_waitcnt vmcnt(1)
; __device__ __forceinline__ unsigned cvt_pk_bf16(float lo, float hi) { f32x2c_t v = {lo, hi}; bf16x2c_t b = __builtin_convertvector(v, bf16x2c_t); return __builtin_bit_cast(unsigned, b); }
; __device__ __forceinline__ f32x4 bf4_lo(u32x4 w) { return (f32x4){__uint_as_float(w.x << 16), __uint_as_float(w.x & 0xffff0000u), __uint_as_float(w.y << 16), __uint_as_float(w.y & 0xffff0000u)}; }
; __device__ __forceinline__ f32x4 bf4_hi(u32x4 w) { return (f32x4){__uint_as_float(w.z << 16), __uint_as_float(w.z & 0xffff0000u), __uint_as_float(w.w << 16), __uint_as_float(w.w & 0xffff0000u)}; }
;     __device__ __forceinline__ void operator()(const f32x4 (&acc)[2][2][4][2], const Unit& u, int wr, int wc, int fr, int fq) const {
;     ...
;         for (int ai = 0; ai < 2; ++ai)
; #pragma unroll
;             for (int m = 0; m < 4; ++m) { const int row = row0 + ai * HALF + m * 16; const size_t off = (size_t)row * 1024 + col0; float rs = 1.f; if constexpr (MIX) { const float* sp = rs2 + 4 * row + 2; rs = 1.0f / sqrtf((sp[0] + sp[1]) * (1.f / 512.f) + NEPS); }
; #pragma unroll
;                 for (int bj = 0; bj < 2; ++bj) { f32x4 x0, x1;
;                     if constexpr (XF32) { x0 = *(const f32x4*)((const float*)xin + off + bj * HALF); x1 = *(const f32x4*)((const float*)xin + off + bj * HALF + 4); }
;                     else { const u32x4 w = xw[ai][m][bj]; x0 = bf4_lo(w); x1 = bf4_hi(w); }
;                     const f32x4 o0 = x0 + gv[bj][0] * (acc[ai][bj][m][0] * rs), o1 = x1 + gv[bj][1] * (acc[ai][bj][m][1] * rs);
;                     u32x4 w; w.x = cvt_pk_bf16(o0[0], o0[1]); w.y = cvt_pk_bf16(o0[2], o0[3]); w.z = cvt_pk_bf16(o1[0], o1[1]); w.w = cvt_pk_bf16(o1[2], o1[3]);
;                     *(u32x4*)(xout + off + bj * HALF) = w; } }
	v_pk_fma_f32 v[78:79], v[78:79], v[144:145], v[82:83]
	v_pk_fma_f32 v[76:77], v[76:77], v[146:147], v[80:81]
	s_waitcnt vmcnt(0)
	v_pk_fma_f32 v[80:81], v[74:75], v[148:149], v[86:87]
	v_pk_fma_f32 v[74:75], v[72:73], v[150:151], v[84:85]
	v_cvt_pk_bf16_f32 v72, v76, v77
	v_cvt_pk_bf16_f32 v73, v78, v79
	v_cvt_pk_bf16_f32 v74, v74, v75
	v_cvt_pk_bf16_f32 v75, v80, v81
	global_store_dwordx4 v[88:89], v[72:75], off sc1
	global_load_dwordx4 v[72:75], v[98:99], off offset:512
	s_nop 0
	global_load_dwordx4 v[76:79], v[98:99], off offset:528
	v_lshl_add_u64 v[80:81], v[152:153], 0, s[38:39]
	v_lshl_add_u64 v[82:83], v[80:81], 2, s[52:53]
	s_mov_b64 s[38:39], 0x24000
	s_waitcnt vmcnt(1)
	v_pk_fma_f32 v[70:71], v[70:71], v[120:121], v[74:75]
	v_pk_fma_f32 v[68:69], v[68:69], v[122:123], v[72:73]
	s_waitcnt vmcnt(0)
	v_pk_fma_f32 v[72:73], v[66:67], v[124:125], v[78:79]
	v_pk_fma_f32 v[66:67], v[64:65], v[126:127], v[76:77]
	v_cvt_pk_bf16_f32 v64, v68, v69
	v_cvt_pk_bf16_f32 v65, v70, v71
	v_cvt_pk_bf16_f32 v66, v66, v67
	v_cvt_pk_bf16_f32 v67, v72, v73
	global_store_dwordx4 v[88:89], v[64:67], off offset:256 sc1
	global_load_dwordx4 v[64:67], v[82:83], off
	s_nop 0
	global_load_dwordx4 v[68:71], v[82:83], off offset:16
	v_lshl_add_u64 v[72:73], v[80:81], 1, s[24:25]
	s_waitcnt vmcnt(1)
	v_pk_fma_f32 v[62:63], v[62:63], v[144:145], v[66:67]
	v_pk_fma_f32 v[60:61], v[60:61], v[146:147], v[64:65]
	s_waitcnt vmcnt(0)
	v_pk_fma_f32 v[64:65], v[58:59], v[148:149], v[70:71]
	v_pk_fma_f32 v[58:59], v[56:57], v[150:151], v[68:69]
	v_cvt_pk_bf16_f32 v56, v60, v61
	v_cvt_pk_bf16_f32 v57, v62, v63
	v_cvt_pk_bf16_f32 v58, v58, v59
	v_cvt_pk_bf16_f32 v59, v64, v65
	global_store_dwordx4 v[72:73], v[56:59], off sc1
	global_load_dwordx4 v[56:59], v[82:83], off offset:512
	s_nop 0
	global_load_dwordx4 v[60:63], v[82:83], off offset:528
	v_lshl_add_u64 v[64:65], v[152:153], 0, s[38:39]
	v_lshl_add_u64 v[66:67], v[64:65], 2, s[52:53]
	s_mov_b64 s[38:39], 0x28000
	s_waitcnt vmcnt(1)
	v_pk_fma_f32 v[54:55], v[54:55], v[120:121], v[58:59]
	v_pk_fma_f32 v[52:53], v[52:53], v[122:123], v[56:57]
	s_waitcnt vmcnt(0)
	v_pk_fma_f32 v[56:57], v[50:51], v[124:125], v[62:63]
	v_pk_fma_f32 v[50:51], v[48:49], v[126:127], v[60:61]
	v_cvt_pk_bf16_f32 v48, v52, v53
	v_cvt_pk_bf16_f32 v49, v54, v55
	v_cvt_pk_bf16_f32 v50, v50, v51
	v_cvt_pk_bf16_f32 v51, v56, v57
	global_store_dwordx4 v[72:73], v[48:51], off offset:256 sc1
	global_load_dwordx4 v[48:51], v[66:67], off
	s_nop 0
	global_load_dwordx4 v[52:55], v[66:67], off offset:16
	v_lshl_add_u64 v[56:57], v[64:65], 1, s[24:25]
	s_waitcnt vmcnt(1)
	v_pk_fma_f32 v[46:47], v[46:47], v[144:145], v[50:51]
	v_pk_fma_f32 v[44:45], v[44:45], v[146:147], v[48:49]
	s_waitcnt vmcnt(0)
	v_pk_fma_f32 v[48:49], v[42:43], v[148:149], v[54:55]
	v_pk_fma_f32 v[42:43], v[40:41], v[150:151], v[52:53]
	v_cvt_pk_bf16_f32 v40, v44, v45
	v_cvt_pk_bf16_f32 v41, v46, v47
	v_cvt_pk_bf16_f32 v42, v42, v43
	v_cvt_pk_bf16_f32 v43, v48, v49
	global_store_dwordx4 v[56:57], v[40:43], off sc1
	global_load_dwordx4 v[40:43], v[66:67], off offset:512
	s_nop 0
	global_load_dwordx4 v[44:47], v[66:67], off offset:528
	v_lshl_add_u64 v[48:49], v[152:153], 0, s[38:39]
	v_lshl_add_u64 v[50:51], v[48:49], 2, s[52:53]
	s_mov_b64 s[38:39], 0x2c000
	s_waitcnt vmcnt(1)
	v_pk_fma_f32 v[38:39], v[38:39], v[120:121], v[42:43]
	v_pk_fma_f32 v[36:37], v[36:37], v[122:123], v[40:41]
	s_waitcnt vmcnt(0)
	v_pk_fma_f32 v[40:41], v[34:35], v[124:125], v[46:47]
	v_pk_fma_f32 v[34:35], v[32:33], v[126:127], v[44:45]
	v_cvt_pk_bf16_f32 v32, v36, v37
	v_cvt_pk_bf16_f32 v33, v38, v39
	v_cvt_pk_bf16_f32 v34, v34, v35
	v_cvt_pk_bf16_f32 v35, v40, v41
	global_store_dwordx4 v[56:57], v[32:35], off offset:256 sc1
	global_load_dwordx4 v[32:35], v[50:51], off
	s_nop 0
	global_load_dwordx4 v[36:39], v[50:51], off offset:16
	v_lshl_add_u64 v[40:41], v[48:49], 1, s[24:25]
	s_waitcnt vmcnt(1)
	v_pk_fma_f32 v[30:31], v[30:31], v[144:145], v[34:35]
	v_pk_fma_f32 v[28:29], v[28:29], v[146:147], v[32:33]
	s_waitcnt vmcnt(0)
	v_pk_fma_f32 v[32:33], v[26:27], v[148:149], v[38:39]
	v_pk_fma_f32 v[26:27], v[24:25], v[150:151], v[36:37]
	v_cvt_pk_bf16_f32 v24, v28, v29
	v_cvt_pk_bf16_f32 v25, v30, v31
	v_cvt_pk_bf16_f32 v26, v26, v27
	v_cvt_pk_bf16_f32 v27, v32, v33
	global_store_dwordx4 v[40:41], v[24:27], off sc1
	global_load_dwordx4 v[24:27], v[50:51], off offset:512
	s_nop 0
	global_load_dwordx4 v[28:31], v[50:51], off offset:528
	v_lshl_add_u64 v[32:33], v[152:153], 0, s[38:39]
	v_lshl_add_u64 v[34:35], v[32:33], 2, s[52:53]
	s_waitcnt vmcnt(1)
	v_pk_fma_f32 v[22:23], v[22:23], v[120:121], v[26:27]
	v_pk_fma_f32 v[20:21], v[20:21], v[122:123], v[24:25]
	s_waitcnt vmcnt(0)
	v_pk_fma_f32 v[24:25], v[18:19], v[124:125], v[30:31]
	v_pk_fma_f32 v[18:19], v[16:17], v[126:127], v[28:29]
	v_cvt_pk_bf16_f32 v16, v20, v21
	v_cvt_pk_bf16_f32 v17, v22, v23
	v_cvt_pk_bf16_f32 v18, v18, v19
	v_cvt_pk_bf16_f32 v19, v24, v25
	global_store_dwordx4 v[40:41], v[16:19], off offset:256 sc1
	global_load_dwordx4 v[16:19], v[34:35], off
	s_nop 0
	global_load_dwordx4 v[20:23], v[34:35], off offset:16
	v_lshl_add_u64 v[24:25], v[32:33], 1, s[24:25]
	s_waitcnt vmcnt(1)
	v_pk_fma_f32 v[14:15], v[14:15], v[144:145], v[18:19]
	v_pk_fma_f32 v[12:13], v[12:13], v[146:147], v[16:17]
	s_waitcnt vmcnt(0)
	v_pk_fma_f32 v[16:17], v[10:11], v[148:149], v[22:23]
	v_pk_fma_f32 v[10:11], v[8:9], v[150:151], v[20:21]
	v_cvt_pk_bf16_f32 v8, v12, v13
	v_cvt_pk_bf16_f32 v9, v14, v15
	v_cvt_pk_bf16_f32 v10, v10, v11
	v_cvt_pk_bf16_f32 v11, v16, v17
	global_store_dwordx4 v[24:25], v[8:11], off sc1
	global_load_dwordx4 v[8:11], v[34:35], off offset:512
	s_nop 0
	global_load_dwordx4 v[12:15], v[34:35], off offset:528
	s_waitcnt vmcnt(1)
	v_pk_fma_f32 v[6:7], v[6:7], v[120:121], v[10:11]
	v_pk_fma_f32 v[4:5], v[4:5], v[122:123], v[8:9]
	s_waitcnt vmcnt(0)
	v_pk_fma_f32 v[8:9], v[2:3], v[124:125], v[14:15]
	v_pk_fma_f32 v[2:3], v[0:1], v[126:127], v[12:13]
	v_cvt_pk_bf16_f32 v0, v4, v5
	v_cvt_pk_bf16_f32 v1, v6, v7
	v_cvt_pk_bf16_f32 v2, v2, v3
	v_cvt_pk_bf16_f32 v3, v8, v9
	global_store_dwordx4 v[24:25], v[0:3], off offset:256 sc1
	s_cbranch_vccnz .LBB0_344
	s_andn2_b64 vcc, exec, s[10:11]
	s_cbranch_vccnz .LBB0_343
	s_barrier
	s_branch .LBB0_343

; __device__ __forceinline__ unsigned cvt_pk_bf16(float lo, float hi) { f32x2c_t v = {lo, hi}; bf16x2c_t b = __builtin_convertvector(v, bf16x2c_t); return __builtin_bit_cast(unsigned, b); }
; __device__ __forceinline__ f32x4 bf4_lo(u32x4 w) { return (f32x4){__uint_as_float(w.x << 16), __uint_as_float(w.x & 0xffff0000u), __uint_as_float(w.y << 16), __uint_as_float(w.y & 0xffff0000u)}; }
;     __device__ __forceinline__ void operator()(const f32x4 (&acc)[2][2][4][2], const Unit& u, int wr, int wc, int fr, int fq) const {
;     ...
;         const int row0 = u.pm * BM + wr * 64 + fr, col0 = u.pn * BM + wc * 32 + 8 * fq, b = u.pm >> 4;
;         f32x4 gv[2][2];
; #pragma unroll
;         for (int bj = 0; bj < 2; ++bj)
; #pragma unroll
;             for (int n = 0; n < 2; ++n) gv[bj][n] = *(const f32x4*)(gate + (size_t)b * NMODC + col0 + bj * HALF + n * 4) * (MIX ? 1.0f : 0.5f);
;         u32x4 xw[2][4][2];
;         if constexpr (!XF32) {
; #pragma unroll
;             for (int ai = 0; ai < 2; ++ai)
; #pragma unroll
;                 for (int m = 0; m < 4; ++m)
; #pragma unroll
;                     for (int bj = 0; bj < 2; ++bj) xw[ai][m][bj] = *(const u32x4*)((const bf16_t*)xin + (size_t)(row0 + ai * HALF + m * 16) * 1024 + col0 + bj * HALF);
;         }
; #pragma unroll
;         for (int ai = 0; ai < 2; ++ai)
; #pragma unroll
;             for (int m = 0; m < 4; ++m) { const int row = row0 + ai * HALF + m * 16; const size_t off = (size_t)row * 1024 + col0; float rs = 1.f; if constexpr (MIX) { const float* sp = rs2 + 4 * row + 2; rs = 1.0f / sqrtf((sp[0] + sp[1]) * (1.f / 512.f) + NEPS); }
; #pragma unroll
;                 for (int bj = 0; bj < 2; ++bj) { f32x4 x0, x1;
;                     if constexpr (XF32) { x0 = *(const f32x4*)((const float*)xin + off + bj * HALF); x1 = *(const f32x4*)((const float*)xin + off + bj * HALF + 4); }
;                     else { const u32x4 w = xw[ai][m][bj]; x0 = bf4_lo(w); x1 = bf4_hi(w); }
;                     const f32x4 o0 = x0 + gv[bj][0] * (acc[ai][bj][m][0] * rs), o1 = x1 + gv[bj][1] * (acc[ai][bj][m][1] * rs);
;                     u32x4 w; w.x = cvt_pk_bf16(o0[0], o0[1]); w.y = cvt_pk_bf16(o0[2], o0[3]); w.z = cvt_pk_bf16(o1[0], o1[1]); w.w = cvt_pk_bf16(o1[2], o1[3]);
;                     *(u32x4*)(xout + off + bj * HALF) = w; } }
.LBB0_903:
	s_lshl_b32 s6, s64, 8
	v_mov_b32_e32 v1, v168
	v_mov_b32_e32 v2, v169
	s_add_i32 s6, s6, s43
	s_lshl_b32 s7, s69, 8
	v_add_u32_e32 v166, s6, v1
	v_lshlrev_b32_e32 v122, 2, v166
	v_ashrrev_i32_e32 v123, 31, v122
	v_lshl_add_u64 v[122:123], v[122:123], 2, s[46:47]
	global_load_dwordx2 v[186:187], v[122:123], off offset:8
	s_or_b32 s7, s7, s54
	v_lshl_add_u32 v120, v2, 3, s7
	v_ashrrev_i32_e32 v121, 31, v120
	s_ashr_i32 s6, s64, 4
	v_lshlrev_b64 v[2:3], 1, v[120:121]
	v_ashrrev_i32_e32 v167, 31, v166
	s_mul_hi_i32 s7, s6, 0x9000
	s_mul_i32 s6, s6, 0x9000
	v_lshl_add_u64 v[164:165], s[24:25], 0, v[2:3]
	v_lshlrev_b64 v[184:185], 11, v[166:167]
	s_add_u32 s6, s37, s6
	v_lshl_add_u64 v[122:123], v[164:165], 0, v[184:185]
	s_addc_u32 s7, s41, s7
	global_load_dwordx4 v[176:179], v[122:123], off
	global_load_dwordx4 v[180:183], v[122:123], off offset:256
	v_lshl_add_u64 v[120:121], v[120:121], 2, s[6:7]
	global_load_dwordx4 v[136:139], v[120:121], off
	global_load_dwordx4 v[132:135], v[120:121], off offset:16
	global_load_dwordx4 v[128:131], v[120:121], off offset:512
	s_nop 0
	global_load_dwordx4 v[120:123], v[120:121], off offset:528
	v_add_u32_e32 v190, 16, v166
	v_ashrrev_i32_e32 v191, 31, v190
	v_lshlrev_b32_e32 v192, 2, v190
	v_lshlrev_b64 v[198:199], 11, v[190:191]
	v_lshl_add_u64 v[184:185], s[24:25], 0, v[184:185]
	v_ashrrev_i32_e32 v193, 31, v192
	v_lshl_add_u64 v[194:195], v[164:165], 0, v[198:199]
	v_lshl_add_u64 v[184:185], v[184:185], 0, v[2:3]
	v_lshl_add_u64 v[200:201], v[192:193], 2, s[46:47]
	global_load_dwordx4 v[190:193], v[194:195], off
	s_nop 0
	global_load_dwordx4 v[194:197], v[194:195], off offset:256
	s_waitcnt vmcnt(0)
	v_add_f32_e32 v1, v186, v187
	v_fmamk_f32 v1, v1, 0x3b000000, v174
	v_mul_f32_e32 v167, 0x4f800000, v1
	v_cmp_gt_f32_e32 vcc, s61, v1
	v_lshlrev_b32_e32 v186, 16, v176
	s_nop 0
	v_cndmask_b32_e32 v1, v1, v167, vcc
	v_sqrt_f32_e32 v167, v1
	v_and_b32_e32 v187, 0xffff0000, v176
	v_lshlrev_b32_e32 v176, 16, v177
	v_and_b32_e32 v177, 0xffff0000, v177
	v_add_u32_e32 v175, -1, v167
	v_add_u32_e32 v208, 1, v167
	v_fma_f32 v209, -v175, v167, v1
	v_fma_f32 v210, -v208, v167, v1
	v_cmp_ge_f32_e64 s[6:7], 0, v209
	v_lshlrev_b32_e32 v202, 16, v178
	v_and_b32_e32 v203, 0xffff0000, v178
	v_cndmask_b32_e64 v167, v167, v175, s[6:7]
	v_cmp_lt_f32_e64 s[6:7], 0, v210
	v_lshlrev_b32_e32 v178, 16, v179
	v_and_b32_e32 v179, 0xffff0000, v179
	v_cndmask_b32_e64 v167, v167, v208, s[6:7]
	v_mul_f32_e32 v175, 0x37800000, v167
	v_cndmask_b32_e32 v167, v167, v175, vcc
	v_cmp_class_f32_e32 vcc, v1, v172
	v_lshlrev_b32_e32 v204, 16, v180
	v_and_b32_e32 v205, 0xffff0000, v180
	v_cndmask_b32_e32 v1, v167, v1, vcc
	v_div_scale_f32 v167, s[6:7], v1, v1, 1.0
	v_rcp_f32_e32 v175, v167
	v_div_scale_f32 v208, vcc, 1.0, v1, 1.0
	v_lshlrev_b32_e32 v180, 16, v181
	v_fma_f32 v209, -v167, v175, 1.0
	v_fmac_f32_e32 v175, v209, v175
	v_mul_f32_e32 v209, v208, v175
	v_fma_f32 v210, -v167, v209, v208
	v_fmac_f32_e32 v209, v210, v175
	v_fma_f32 v167, -v167, v209, v208
	v_div_fmas_f32 v167, v167, v175, v209
	v_div_fixup_f32 v208, v167, v1, 1.0
	v_pk_mul_f32 v[144:145], v[144:145], v[208:209] op_sel_hi:[1,0]
	v_pk_mul_f32 v[146:147], v[146:147], v[208:209] op_sel_hi:[1,0]
	v_pk_mul_f32 v[140:141], v[140:141], v[208:209] op_sel_hi:[1,0]
	v_pk_mul_f32 v[142:143], v[142:143], v[208:209] op_sel_hi:[1,0]
	v_and_b32_e32 v181, 0xffff0000, v181
	v_lshlrev_b32_e32 v206, 16, v182
	v_and_b32_e32 v207, 0xffff0000, v182
	v_lshlrev_b32_e32 v182, 16, v183
	v_and_b32_e32 v183, 0xffff0000, v183
	v_pk_mul_f32 v[124:125], v[124:125], v[208:209] op_sel_hi:[1,0]
	v_pk_mul_f32 v[126:127], v[126:127], v[208:209] op_sel_hi:[1,0]
	v_pk_mul_f32 v[116:117], v[116:117], v[208:209] op_sel_hi:[1,0]
	v_pk_mul_f32 v[118:119], v[118:119], v[208:209] op_sel_hi:[1,0]
	v_pk_fma_f32 v[146:147], v[138:139], v[146:147], v[176:177]
	v_pk_fma_f32 v[144:145], v[136:137], v[144:145], v[186:187]
	v_pk_fma_f32 v[142:143], v[134:135], v[142:143], v[178:179]
	v_pk_fma_f32 v[140:141], v[132:133], v[140:141], v[202:203]
	v_pk_fma_f32 v[126:127], v[130:131], v[126:127], v[180:181]
	v_pk_fma_f32 v[124:125], v[128:129], v[124:125], v[204:205]
	v_pk_fma_f32 v[176:177], v[122:123], v[118:119], v[182:183]
	v_pk_fma_f32 v[178:179], v[120:121], v[116:117], v[206:207]
	v_cvt_pk_bf16_f32 v116, v144, v145
	v_cvt_pk_bf16_f32 v117, v146, v147
	v_cvt_pk_bf16_f32 v118, v140, v141
	v_cvt_pk_bf16_f32 v119, v142, v143
	v_cvt_pk_bf16_f32 v124, v124, v125
	v_cvt_pk_bf16_f32 v125, v126, v127
	v_cvt_pk_bf16_f32 v126, v178, v179
	v_cvt_pk_bf16_f32 v127, v176, v177
	global_store_dwordx4 v[184:185], v[116:119], off sc1
	global_store_dwordx4 v[184:185], v[124:127], off offset:256 sc1
	global_load_dwordx2 v[140:141], v[200:201], off offset:8
	v_lshlrev_b32_e32 v178, 16, v191
	v_and_b32_e32 v179, 0xffff0000, v191
	v_lshlrev_b32_e32 v180, 16, v192
	v_and_b32_e32 v181, 0xffff0000, v192
	v_lshlrev_b32_e32 v182, 16, v193
	v_and_b32_e32 v183, 0xffff0000, v193
	v_lshlrev_b32_e32 v184, 16, v194
	v_and_b32_e32 v185, 0xffff0000, v194
	v_add_u32_e32 v116, 32, v166
	v_ashrrev_i32_e32 v117, 31, v116
	v_lshlrev_b32_e32 v176, 16, v190
	v_and_b32_e32 v177, 0xffff0000, v190
	v_lshlrev_b32_e32 v118, 2, v116
	v_lshlrev_b64 v[142:143], 11, v[116:117]
	v_lshl_add_u64 v[144:145], s[24:25], 0, v[198:199]
	v_lshlrev_b32_e32 v186, 16, v195
	v_and_b32_e32 v187, 0xffff0000, v195
	v_lshlrev_b32_e32 v190, 16, v197
	v_ashrrev_i32_e32 v119, 31, v118
	v_lshl_add_u64 v[124:125], v[164:165], 0, v[142:143]
	v_lshl_add_u64 v[144:145], v[144:145], 0, v[2:3]
	v_lshl_add_u64 v[146:147], v[118:119], 2, s[46:47]
	global_load_dwordx4 v[116:119], v[124:125], off
	s_nop 0
	global_load_dwordx4 v[124:127], v[124:125], off offset:256
	s_waitcnt vmcnt(2)
; __device__ __forceinline__ unsigned cvt_pk_bf16(float lo, float hi) { f32x2c_t v = {lo, hi}; bf16x2c_t b = __builtin_convertvector(v, bf16x2c_t); return __builtin_bit_cast(unsigned, b); }
; __device__ __forceinline__ f32x4 bf4_lo(u32x4 w) { return (f32x4){__uint_as_float(w.x << 16), __uint_as_float(w.x & 0xffff0000u), __uint_as_float(w.y << 16), __uint_as_float(w.y & 0xffff0000u)}; }
; __device__ __forceinline__ f32x4 bf4_hi(u32x4 w) { return (f32x4){__uint_as_float(w.z << 16), __uint_as_float(w.z & 0xffff0000u), __uint_as_float(w.w << 16), __uint_as_float(w.w & 0xffff0000u)}; }
;     __device__ __forceinline__ void operator()(const f32x4 (&acc)[2][2][4][2], const Unit& u, int wr, int wc, int fr, int fq) const {
;     ...
;         for (int ai = 0; ai < 2; ++ai)
; #pragma unroll
;             for (int m = 0; m < 4; ++m) { const int row = row0 + ai * HALF + m * 16; const size_t off = (size_t)row * 1024 + col0; float rs = 1.f; if constexpr (MIX) { const float* sp = rs2 + 4 * row + 2; rs = 1.0f / sqrtf((sp[0] + sp[1]) * (1.f / 512.f) + NEPS); }
; #pragma unroll
;                 for (int bj = 0; bj < 2; ++bj) { f32x4 x0, x1;
;                     if constexpr (XF32) { x0 = *(const f32x4*)((const float*)xin + off + bj * HALF); x1 = *(const f32x4*)((const float*)xin + off + bj * HALF + 4); }
;                     else { const u32x4 w = xw[ai][m][bj]; x0 = bf4_lo(w); x1 = bf4_hi(w); }
;                     const f32x4 o0 = x0 + gv[bj][0] * (acc[ai][bj][m][0] * rs), o1 = x1 + gv[bj][1] * (acc[ai][bj][m][1] * rs);
;                     u32x4 w; w.x = cvt_pk_bf16(o0[0], o0[1]); w.y = cvt_pk_bf16(o0[2], o0[3]); w.z = cvt_pk_bf16(o1[0], o1[1]); w.w = cvt_pk_bf16(o1[2], o1[3]);
;                     *(u32x4*)(xout + off + bj * HALF) = w; } }
	v_add_f32_e32 v1, v140, v141
	v_fmamk_f32 v1, v1, 0x3b000000, v174
	v_mul_f32_e32 v140, 0x4f800000, v1
	v_cmp_gt_f32_e32 vcc, s61, v1
	v_and_b32_e32 v141, 0xffff0000, v196
	s_nop 0
	v_cndmask_b32_e32 v1, v1, v140, vcc
	v_sqrt_f32_e32 v167, v1
	v_lshlrev_b32_e32 v140, 16, v196
	v_add_u32_e32 v175, -1, v167
	v_add_u32_e32 v191, 1, v167
	v_fma_f32 v192, -v175, v167, v1
	v_fma_f32 v193, -v191, v167, v1
	v_cmp_ge_f32_e64 s[6:7], 0, v192
	s_nop 1
	v_cndmask_b32_e64 v167, v167, v175, s[6:7]
	v_cmp_lt_f32_e64 s[6:7], 0, v193
	s_nop 1
	v_cndmask_b32_e64 v167, v167, v191, s[6:7]
	v_mul_f32_e32 v175, 0x37800000, v167
	v_cndmask_b32_e32 v167, v167, v175, vcc
	v_cmp_class_f32_e32 vcc, v1, v172
	v_and_b32_e32 v191, 0xffff0000, v197
	s_nop 0
	v_cndmask_b32_e32 v1, v167, v1, vcc
	v_div_scale_f32 v167, s[6:7], v1, v1, 1.0
	v_rcp_f32_e32 v175, v167
	v_div_scale_f32 v192, vcc, 1.0, v1, 1.0
	v_fma_f32 v193, -v167, v175, 1.0
	v_fmac_f32_e32 v175, v193, v175
	v_mul_f32_e32 v193, v192, v175
	v_fma_f32 v194, -v167, v193, v192
	v_fmac_f32_e32 v193, v194, v175
	v_fma_f32 v167, -v167, v193, v192
	v_div_fmas_f32 v167, v167, v175, v193
	v_div_fixup_f32 v192, v167, v1, 1.0
	v_pk_mul_f32 v[112:113], v[112:113], v[192:193] op_sel_hi:[1,0]
	v_pk_mul_f32 v[114:115], v[114:115], v[192:193] op_sel_hi:[1,0]
	v_pk_mul_f32 v[108:109], v[108:109], v[192:193] op_sel_hi:[1,0]
	v_pk_mul_f32 v[110:111], v[110:111], v[192:193] op_sel_hi:[1,0]
	v_pk_mul_f32 v[104:105], v[104:105], v[192:193] op_sel_hi:[1,0]
	v_pk_mul_f32 v[106:107], v[106:107], v[192:193] op_sel_hi:[1,0]
	v_pk_mul_f32 v[100:101], v[100:101], v[192:193] op_sel_hi:[1,0]
	v_pk_mul_f32 v[102:103], v[102:103], v[192:193] op_sel_hi:[1,0]
	v_pk_fma_f32 v[114:115], v[138:139], v[114:115], v[178:179]
	v_pk_fma_f32 v[112:113], v[136:137], v[112:113], v[176:177]
	v_pk_fma_f32 v[110:111], v[134:135], v[110:111], v[182:183]
	v_pk_fma_f32 v[108:109], v[132:133], v[108:109], v[180:181]
	v_pk_fma_f32 v[106:107], v[130:131], v[106:107], v[186:187]
	v_pk_fma_f32 v[104:105], v[128:129], v[104:105], v[184:185]
	v_pk_fma_f32 v[176:177], v[122:123], v[102:103], v[190:191]
	v_pk_fma_f32 v[140:141], v[120:121], v[100:101], v[140:141]
	v_cvt_pk_bf16_f32 v100, v112, v113
	v_cvt_pk_bf16_f32 v101, v114, v115
	v_cvt_pk_bf16_f32 v102, v108, v109
	v_cvt_pk_bf16_f32 v103, v110, v111
	v_cvt_pk_bf16_f32 v104, v104, v105
	v_cvt_pk_bf16_f32 v105, v106, v107
	v_cvt_pk_bf16_f32 v106, v140, v141
	v_cvt_pk_bf16_f32 v107, v176, v177
	global_store_dwordx4 v[144:145], v[100:103], off sc1
	global_store_dwordx4 v[144:145], v[104:107], off offset:256 sc1
	global_load_dwordx2 v[108:109], v[146:147], off offset:8
	v_add_u32_e32 v100, 48, v166
	v_ashrrev_i32_e32 v101, 31, v100
	v_lshl_add_u64 v[112:113], s[24:25], 0, v[142:143]
	s_waitcnt vmcnt(4)
	v_lshlrev_b32_e32 v140, 16, v116
	v_and_b32_e32 v141, 0xffff0000, v116
	v_lshlrev_b32_e32 v116, 16, v117
	v_and_b32_e32 v117, 0xffff0000, v117
	v_lshlrev_b32_e32 v142, 16, v118
	v_and_b32_e32 v143, 0xffff0000, v118
	v_lshlrev_b32_e32 v118, 16, v119
	v_and_b32_e32 v119, 0xffff0000, v119
	v_lshlrev_b32_e32 v102, 2, v100
	v_lshlrev_b64 v[110:111], 11, v[100:101]
	s_waitcnt vmcnt(3)
	v_lshlrev_b32_e32 v144, 16, v124
	v_and_b32_e32 v145, 0xffff0000, v124
	v_lshlrev_b32_e32 v124, 16, v125
	v_and_b32_e32 v125, 0xffff0000, v125
	v_ashrrev_i32_e32 v103, 31, v102
	v_lshl_add_u64 v[104:105], v[164:165], 0, v[110:111]
	v_lshl_add_u64 v[112:113], v[112:113], 0, v[2:3]
	v_lshl_add_u64 v[114:115], v[102:103], 2, s[46:47]
	global_load_dwordx4 v[100:103], v[104:105], off
	s_nop 0
	global_load_dwordx4 v[104:107], v[104:105], off offset:256
	s_waitcnt vmcnt(2)
	v_add_f32_e32 v1, v108, v109
	v_fmamk_f32 v1, v1, 0x3b000000, v174
	v_mul_f32_e32 v108, 0x4f800000, v1
	v_cmp_gt_f32_e32 vcc, s61, v1
	v_and_b32_e32 v109, 0xffff0000, v126
	s_nop 0
	v_cndmask_b32_e32 v1, v1, v108, vcc
	v_sqrt_f32_e32 v146, v1
	v_lshlrev_b32_e32 v108, 16, v126
	v_lshlrev_b32_e32 v126, 16, v127
	v_and_b32_e32 v127, 0xffff0000, v127
	v_add_u32_e32 v147, -1, v146
	v_add_u32_e32 v167, 1, v146
	v_fma_f32 v175, -v147, v146, v1
	v_fma_f32 v176, -v167, v146, v1
	v_cmp_ge_f32_e64 s[6:7], 0, v175
	s_nop 1
	v_cndmask_b32_e64 v146, v146, v147, s[6:7]
	v_cmp_lt_f32_e64 s[6:7], 0, v176
	s_nop 1
	v_cndmask_b32_e64 v146, v146, v167, s[6:7]
	v_mul_f32_e32 v147, 0x37800000, v146
	v_cndmask_b32_e32 v146, v146, v147, vcc
	v_cmp_class_f32_e32 vcc, v1, v172
	s_nop 1
	v_cndmask_b32_e32 v1, v146, v1, vcc
	v_div_scale_f32 v146, s[6:7], v1, v1, 1.0
	v_rcp_f32_e32 v147, v146
	v_div_scale_f32 v167, vcc, 1.0, v1, 1.0
	v_fma_f32 v175, -v146, v147, 1.0
	v_fmac_f32_e32 v147, v175, v147
	v_mul_f32_e32 v175, v167, v147
	v_fma_f32 v176, -v146, v175, v167
	v_fmac_f32_e32 v175, v176, v147
	v_fma_f32 v146, -v146, v175, v167
	v_div_fmas_f32 v146, v146, v147, v175
	v_div_fixup_f32 v146, v146, v1, 1.0
	v_pk_mul_f32 v[96:97], v[96:97], v[146:147] op_sel_hi:[1,0]
	v_pk_mul_f32 v[98:99], v[98:99], v[146:147] op_sel_hi:[1,0]
	v_pk_mul_f32 v[92:93], v[92:93], v[146:147] op_sel_hi:[1,0]
	v_pk_mul_f32 v[94:95], v[94:95], v[146:147] op_sel_hi:[1,0]
	v_pk_mul_f32 v[88:89], v[88:89], v[146:147] op_sel_hi:[1,0]
	v_pk_mul_f32 v[90:91], v[90:91], v[146:147] op_sel_hi:[1,0]
	v_pk_mul_f32 v[84:85], v[84:85], v[146:147] op_sel_hi:[1,0]
	v_pk_mul_f32 v[86:87], v[86:87], v[146:147] op_sel_hi:[1,0]
	v_pk_fma_f32 v[98:99], v[138:139], v[98:99], v[116:117]
	v_pk_fma_f32 v[96:97], v[136:137], v[96:97], v[140:141]
	v_pk_fma_f32 v[94:95], v[134:135], v[94:95], v[118:119]
	v_pk_fma_f32 v[92:93], v[132:133], v[92:93], v[142:143]
	v_pk_fma_f32 v[90:91], v[130:131], v[90:91], v[124:125]
	v_pk_fma_f32 v[88:89], v[128:129], v[88:89], v[144:145]
	v_pk_fma_f32 v[116:117], v[122:123], v[86:87], v[126:127]
	v_pk_fma_f32 v[108:109], v[120:121], v[84:85], v[108:109]
	v_cvt_pk_bf16_f32 v84, v96, v97
	v_cvt_pk_bf16_f32 v85, v98, v99
	v_cvt_pk_bf16_f32 v86, v92, v93
	v_cvt_pk_bf16_f32 v87, v94, v95
	v_cvt_pk_bf16_f32 v88, v88, v89
	v_cvt_pk_bf16_f32 v89, v90, v91
	v_cvt_pk_bf16_f32 v90, v108, v109
	v_cvt_pk_bf16_f32 v91, v116, v117
	global_store_dwordx4 v[112:113], v[84:87], off sc1
	global_store_dwordx4 v[112:113], v[88:91], off offset:256 sc1
	global_load_dwordx2 v[92:93], v[114:115], off offset:8
	v_add_u32_e32 v84, 0x80, v166
	v_ashrrev_i32_e32 v85, 31, v84
	v_lshl_add_u64 v[96:97], s[24:25], 0, v[110:111]
	s_waitcnt vmcnt(4)
; __device__ __forceinline__ unsigned cvt_pk_bf16(float lo, float hi) { f32x2c_t v = {lo, hi}; bf16x2c_t b = __builtin_convertvector(v, bf16x2c_t); return __builtin_bit_cast(unsigned, b); }
; __device__ __forceinline__ f32x4 bf4_lo(u32x4 w) { return (f32x4){__uint_as_float(w.x << 16), __uint_as_float(w.x & 0xffff0000u), __uint_as_float(w.y << 16), __uint_as_float(w.y & 0xffff0000u)}; }
; __device__ __forceinline__ f32x4 bf4_hi(u32x4 w) { return (f32x4){__uint_as_float(w.z << 16), __uint_as_float(w.z & 0xffff0000u), __uint_as_float(w.w << 16), __uint_as_float(w.w & 0xffff0000u)}; }
;     __device__ __forceinline__ void operator()(const f32x4 (&acc)[2][2][4][2], const Unit& u, int wr, int wc, int fr, int fq) const {
;     ...
;         for (int ai = 0; ai < 2; ++ai)
; #pragma unroll
;             for (int m = 0; m < 4; ++m) { const int row = row0 + ai * HALF + m * 16; const size_t off = (size_t)row * 1024 + col0; float rs = 1.f; if constexpr (MIX) { const float* sp = rs2 + 4 * row + 2; rs = 1.0f / sqrtf((sp[0] + sp[1]) * (1.f / 512.f) + NEPS); }
; #pragma unroll
;                 for (int bj = 0; bj < 2; ++bj) { f32x4 x0, x1;
;                     if constexpr (XF32) { x0 = *(const f32x4*)((const float*)xin + off + bj * HALF); x1 = *(const f32x4*)((const float*)xin + off + bj * HALF + 4); }
;                     else { const u32x4 w = xw[ai][m][bj]; x0 = bf4_lo(w); x1 = bf4_hi(w); }
;                     const f32x4 o0 = x0 + gv[bj][0] * (acc[ai][bj][m][0] * rs), o1 = x1 + gv[bj][1] * (acc[ai][bj][m][1] * rs);
;                     u32x4 w; w.x = cvt_pk_bf16(o0[0], o0[1]); w.y = cvt_pk_bf16(o0[2], o0[3]); w.z = cvt_pk_bf16(o1[0], o1[1]); w.w = cvt_pk_bf16(o1[2], o1[3]);
;                     *(u32x4*)(xout + off + bj * HALF) = w; } }
	v_lshlrev_b32_e32 v108, 16, v100
	v_and_b32_e32 v109, 0xffff0000, v100
	v_lshlrev_b32_e32 v100, 16, v101
	v_and_b32_e32 v101, 0xffff0000, v101
	v_lshlrev_b32_e32 v110, 16, v102
	v_and_b32_e32 v111, 0xffff0000, v102
	v_lshlrev_b32_e32 v102, 16, v103
	v_and_b32_e32 v103, 0xffff0000, v103
	v_lshlrev_b32_e32 v86, 2, v84
	v_lshlrev_b64 v[94:95], 11, v[84:85]
	s_waitcnt vmcnt(3)
	v_lshlrev_b32_e32 v112, 16, v104
	v_and_b32_e32 v113, 0xffff0000, v104
	v_lshlrev_b32_e32 v104, 16, v105
	v_and_b32_e32 v105, 0xffff0000, v105
	v_ashrrev_i32_e32 v87, 31, v86
	v_lshl_add_u64 v[88:89], v[164:165], 0, v[94:95]
	v_lshl_add_u64 v[96:97], v[96:97], 0, v[2:3]
	v_lshl_add_u64 v[98:99], v[86:87], 2, s[46:47]
	global_load_dwordx4 v[84:87], v[88:89], off
	s_nop 0
	global_load_dwordx4 v[88:91], v[88:89], off offset:256
	s_waitcnt vmcnt(2)
	v_add_f32_e32 v1, v92, v93
	v_fmamk_f32 v1, v1, 0x3b000000, v174
	v_mul_f32_e32 v92, 0x4f800000, v1
	v_cmp_gt_f32_e32 vcc, s61, v1
	v_and_b32_e32 v93, 0xffff0000, v106
	s_nop 0
	v_cndmask_b32_e32 v1, v1, v92, vcc
	v_sqrt_f32_e32 v114, v1
	v_lshlrev_b32_e32 v92, 16, v106
	v_lshlrev_b32_e32 v106, 16, v107
	v_and_b32_e32 v107, 0xffff0000, v107
	v_add_u32_e32 v115, -1, v114
	v_add_u32_e32 v116, 1, v114
	v_fma_f32 v117, -v115, v114, v1
	v_fma_f32 v118, -v116, v114, v1
	v_cmp_ge_f32_e64 s[6:7], 0, v117
	s_nop 1
	v_cndmask_b32_e64 v114, v114, v115, s[6:7]
	v_cmp_lt_f32_e64 s[6:7], 0, v118
	s_nop 1
	v_cndmask_b32_e64 v114, v114, v116, s[6:7]
	v_mul_f32_e32 v115, 0x37800000, v114
	v_cndmask_b32_e32 v114, v114, v115, vcc
	v_cmp_class_f32_e32 vcc, v1, v172
	s_nop 1
	v_cndmask_b32_e32 v1, v114, v1, vcc
	v_div_scale_f32 v114, s[6:7], v1, v1, 1.0
	v_rcp_f32_e32 v115, v114
	v_div_scale_f32 v116, vcc, 1.0, v1, 1.0
	v_fma_f32 v117, -v114, v115, 1.0
	v_fmac_f32_e32 v115, v117, v115
	v_mul_f32_e32 v117, v116, v115
	v_fma_f32 v118, -v114, v117, v116
	v_fmac_f32_e32 v117, v118, v115
	v_fma_f32 v114, -v114, v117, v116
	v_div_fmas_f32 v114, v114, v115, v117
	v_div_fixup_f32 v114, v114, v1, 1.0
	v_pk_mul_f32 v[80:81], v[80:81], v[114:115] op_sel_hi:[1,0]
	v_pk_mul_f32 v[82:83], v[82:83], v[114:115] op_sel_hi:[1,0]
	v_pk_mul_f32 v[76:77], v[76:77], v[114:115] op_sel_hi:[1,0]
	v_pk_mul_f32 v[78:79], v[78:79], v[114:115] op_sel_hi:[1,0]
	v_pk_mul_f32 v[72:73], v[72:73], v[114:115] op_sel_hi:[1,0]
	v_pk_mul_f32 v[74:75], v[74:75], v[114:115] op_sel_hi:[1,0]
	v_pk_mul_f32 v[68:69], v[68:69], v[114:115] op_sel_hi:[1,0]
	v_pk_mul_f32 v[70:71], v[70:71], v[114:115] op_sel_hi:[1,0]
	v_pk_fma_f32 v[82:83], v[138:139], v[82:83], v[100:101]
	v_pk_fma_f32 v[80:81], v[136:137], v[80:81], v[108:109]
	v_pk_fma_f32 v[78:79], v[134:135], v[78:79], v[102:103]
	v_pk_fma_f32 v[76:77], v[132:133], v[76:77], v[110:111]
	v_pk_fma_f32 v[74:75], v[130:131], v[74:75], v[104:105]
	v_pk_fma_f32 v[72:73], v[128:129], v[72:73], v[112:113]
	v_pk_fma_f32 v[100:101], v[122:123], v[70:71], v[106:107]
	v_pk_fma_f32 v[92:93], v[120:121], v[68:69], v[92:93]
	v_cvt_pk_bf16_f32 v68, v80, v81
	v_cvt_pk_bf16_f32 v69, v82, v83
	v_cvt_pk_bf16_f32 v70, v76, v77
	v_cvt_pk_bf16_f32 v71, v78, v79
	v_cvt_pk_bf16_f32 v72, v72, v73
	v_cvt_pk_bf16_f32 v73, v74, v75
	v_cvt_pk_bf16_f32 v74, v92, v93
	v_cvt_pk_bf16_f32 v75, v100, v101
	global_store_dwordx4 v[96:97], v[68:71], off sc1
	global_store_dwordx4 v[96:97], v[72:75], off offset:256 sc1
	global_load_dwordx2 v[76:77], v[98:99], off offset:8
	v_add_u32_e32 v68, 0x90, v166
	v_ashrrev_i32_e32 v69, 31, v68
	v_lshl_add_u64 v[80:81], s[24:25], 0, v[94:95]
	s_waitcnt vmcnt(4)
	v_lshlrev_b32_e32 v92, 16, v84
	v_and_b32_e32 v93, 0xffff0000, v84
	v_lshlrev_b32_e32 v84, 16, v85
	v_and_b32_e32 v85, 0xffff0000, v85
	v_lshlrev_b32_e32 v94, 16, v86
	v_and_b32_e32 v95, 0xffff0000, v86
	v_lshlrev_b32_e32 v86, 16, v87
	v_and_b32_e32 v87, 0xffff0000, v87
	v_lshlrev_b32_e32 v70, 2, v68
	v_lshlrev_b64 v[78:79], 11, v[68:69]
	s_waitcnt vmcnt(3)
	v_lshlrev_b32_e32 v96, 16, v88
	v_and_b32_e32 v97, 0xffff0000, v88
	v_lshlrev_b32_e32 v88, 16, v89
	v_and_b32_e32 v89, 0xffff0000, v89
	v_ashrrev_i32_e32 v71, 31, v70
	v_lshl_add_u64 v[72:73], v[164:165], 0, v[78:79]
	v_lshl_add_u64 v[80:81], v[80:81], 0, v[2:3]
	v_lshl_add_u64 v[82:83], v[70:71], 2, s[46:47]
	global_load_dwordx4 v[68:71], v[72:73], off
	s_nop 0
	global_load_dwordx4 v[72:75], v[72:73], off offset:256
	s_waitcnt vmcnt(2)
	v_add_f32_e32 v1, v76, v77
	v_fmamk_f32 v1, v1, 0x3b000000, v174
	v_mul_f32_e32 v76, 0x4f800000, v1
	v_cmp_gt_f32_e32 vcc, s61, v1
	v_and_b32_e32 v77, 0xffff0000, v90
	s_nop 0
	v_cndmask_b32_e32 v1, v1, v76, vcc
	v_sqrt_f32_e32 v98, v1
	v_lshlrev_b32_e32 v76, 16, v90
	v_lshlrev_b32_e32 v90, 16, v91
	v_and_b32_e32 v91, 0xffff0000, v91
	v_add_u32_e32 v99, -1, v98
	v_add_u32_e32 v100, 1, v98
	v_fma_f32 v101, -v99, v98, v1
	v_fma_f32 v102, -v100, v98, v1
	v_cmp_ge_f32_e64 s[6:7], 0, v101
	s_nop 1
	v_cndmask_b32_e64 v98, v98, v99, s[6:7]
	v_cmp_lt_f32_e64 s[6:7], 0, v102
	s_nop 1
	v_cndmask_b32_e64 v98, v98, v100, s[6:7]
	v_mul_f32_e32 v99, 0x37800000, v98
	v_cndmask_b32_e32 v98, v98, v99, vcc
	v_cmp_class_f32_e32 vcc, v1, v172
	s_nop 1
	v_cndmask_b32_e32 v1, v98, v1, vcc
	v_div_scale_f32 v98, s[6:7], v1, v1, 1.0
	v_rcp_f32_e32 v99, v98
	v_div_scale_f32 v100, vcc, 1.0, v1, 1.0
	v_fma_f32 v101, -v98, v99, 1.0
	v_fmac_f32_e32 v99, v101, v99
	v_mul_f32_e32 v101, v100, v99
	v_fma_f32 v102, -v98, v101, v100
	v_fmac_f32_e32 v101, v102, v99
	v_fma_f32 v98, -v98, v101, v100
	v_div_fmas_f32 v98, v98, v99, v101
	v_div_fixup_f32 v98, v98, v1, 1.0
	v_pk_mul_f32 v[64:65], v[64:65], v[98:99] op_sel_hi:[1,0]
	v_pk_mul_f32 v[66:67], v[66:67], v[98:99] op_sel_hi:[1,0]
	v_pk_mul_f32 v[60:61], v[60:61], v[98:99] op_sel_hi:[1,0]
	v_pk_mul_f32 v[62:63], v[62:63], v[98:99] op_sel_hi:[1,0]
	v_pk_mul_f32 v[56:57], v[56:57], v[98:99] op_sel_hi:[1,0]
	v_pk_mul_f32 v[58:59], v[58:59], v[98:99] op_sel_hi:[1,0]
	v_pk_mul_f32 v[52:53], v[52:53], v[98:99] op_sel_hi:[1,0]
	v_pk_mul_f32 v[54:55], v[54:55], v[98:99] op_sel_hi:[1,0]
	v_pk_fma_f32 v[66:67], v[138:139], v[66:67], v[84:85]
	v_pk_fma_f32 v[64:65], v[136:137], v[64:65], v[92:93]
	v_pk_fma_f32 v[62:63], v[134:135], v[62:63], v[86:87]
	v_pk_fma_f32 v[60:61], v[132:133], v[60:61], v[94:95]
	v_pk_fma_f32 v[58:59], v[130:131], v[58:59], v[88:89]
	v_pk_fma_f32 v[56:57], v[128:129], v[56:57], v[96:97]
	v_pk_fma_f32 v[84:85], v[122:123], v[54:55], v[90:91]
	v_pk_fma_f32 v[76:77], v[120:121], v[52:53], v[76:77]
	v_cvt_pk_bf16_f32 v52, v64, v65
	v_cvt_pk_bf16_f32 v53, v66, v67
	v_cvt_pk_bf16_f32 v54, v60, v61
	v_cvt_pk_bf16_f32 v55, v62, v63
	v_cvt_pk_bf16_f32 v56, v56, v57
	v_cvt_pk_bf16_f32 v57, v58, v59
	v_cvt_pk_bf16_f32 v58, v76, v77
	v_cvt_pk_bf16_f32 v59, v84, v85
	global_store_dwordx4 v[80:81], v[52:55], off sc1
	global_store_dwordx4 v[80:81], v[56:59], off offset:256 sc1
	global_load_dwordx2 v[60:61], v[82:83], off offset:8
	v_add_u32_e32 v52, 0xa0, v166
	v_ashrrev_i32_e32 v53, 31, v52
	v_lshl_add_u64 v[64:65], s[24:25], 0, v[78:79]
	s_waitcnt vmcnt(4)
; __device__ __forceinline__ unsigned cvt_pk_bf16(float lo, float hi) { f32x2c_t v = {lo, hi}; bf16x2c_t b = __builtin_convertvector(v, bf16x2c_t); return __builtin_bit_cast(unsigned, b); }
; __device__ __forceinline__ f32x4 bf4_lo(u32x4 w) { return (f32x4){__uint_as_float(w.x << 16), __uint_as_float(w.x & 0xffff0000u), __uint_as_float(w.y << 16), __uint_as_float(w.y & 0xffff0000u)}; }
; __device__ __forceinline__ f32x4 bf4_hi(u32x4 w) { return (f32x4){__uint_as_float(w.z << 16), __uint_as_float(w.z & 0xffff0000u), __uint_as_float(w.w << 16), __uint_as_float(w.w & 0xffff0000u)}; }
;     __device__ __forceinline__ void operator()(const f32x4 (&acc)[2][2][4][2], const Unit& u, int wr, int wc, int fr, int fq) const {
;     ...
;         for (int ai = 0; ai < 2; ++ai)
; #pragma unroll
;             for (int m = 0; m < 4; ++m) { const int row = row0 + ai * HALF + m * 16; const size_t off = (size_t)row * 1024 + col0; float rs = 1.f; if constexpr (MIX) { const float* sp = rs2 + 4 * row + 2; rs = 1.0f / sqrtf((sp[0] + sp[1]) * (1.f / 512.f) + NEPS); }
; #pragma unroll
;                 for (int bj = 0; bj < 2; ++bj) { f32x4 x0, x1;
;                     if constexpr (XF32) { x0 = *(const f32x4*)((const float*)xin + off + bj * HALF); x1 = *(const f32x4*)((const float*)xin + off + bj * HALF + 4); }
;                     else { const u32x4 w = xw[ai][m][bj]; x0 = bf4_lo(w); x1 = bf4_hi(w); }
;                     const f32x4 o0 = x0 + gv[bj][0] * (acc[ai][bj][m][0] * rs), o1 = x1 + gv[bj][1] * (acc[ai][bj][m][1] * rs);
;                     u32x4 w; w.x = cvt_pk_bf16(o0[0], o0[1]); w.y = cvt_pk_bf16(o0[2], o0[3]); w.z = cvt_pk_bf16(o1[0], o1[1]); w.w = cvt_pk_bf16(o1[2], o1[3]);
;                     *(u32x4*)(xout + off + bj * HALF) = w; } }
	v_lshlrev_b32_e32 v76, 16, v68
	v_and_b32_e32 v77, 0xffff0000, v68
	v_lshlrev_b32_e32 v68, 16, v69
	v_and_b32_e32 v69, 0xffff0000, v69
	v_lshlrev_b32_e32 v78, 16, v70
	v_and_b32_e32 v79, 0xffff0000, v70
	v_lshlrev_b32_e32 v70, 16, v71
	v_and_b32_e32 v71, 0xffff0000, v71
	v_lshlrev_b32_e32 v54, 2, v52
	v_lshlrev_b64 v[62:63], 11, v[52:53]
	s_waitcnt vmcnt(3)
	v_lshlrev_b32_e32 v80, 16, v72
	v_and_b32_e32 v81, 0xffff0000, v72
	v_lshlrev_b32_e32 v72, 16, v73
	v_and_b32_e32 v73, 0xffff0000, v73
	v_ashrrev_i32_e32 v55, 31, v54
	v_lshl_add_u64 v[56:57], v[164:165], 0, v[62:63]
	v_lshl_add_u64 v[64:65], v[64:65], 0, v[2:3]
	v_lshl_add_u64 v[66:67], v[54:55], 2, s[46:47]
	global_load_dwordx4 v[52:55], v[56:57], off
	s_nop 0
	global_load_dwordx4 v[56:59], v[56:57], off offset:256
	s_waitcnt vmcnt(2)
	v_add_f32_e32 v1, v60, v61
	v_fmamk_f32 v1, v1, 0x3b000000, v174
	v_mul_f32_e32 v60, 0x4f800000, v1
	v_cmp_gt_f32_e32 vcc, s61, v1
	v_and_b32_e32 v61, 0xffff0000, v74
	s_nop 0
	v_cndmask_b32_e32 v1, v1, v60, vcc
	v_sqrt_f32_e32 v82, v1
	v_lshlrev_b32_e32 v60, 16, v74
	v_lshlrev_b32_e32 v74, 16, v75
	v_and_b32_e32 v75, 0xffff0000, v75
	v_add_u32_e32 v83, -1, v82
	v_add_u32_e32 v84, 1, v82
	v_fma_f32 v85, -v83, v82, v1
	v_fma_f32 v86, -v84, v82, v1
	v_cmp_ge_f32_e64 s[6:7], 0, v85
	s_nop 1
	v_cndmask_b32_e64 v82, v82, v83, s[6:7]
	v_cmp_lt_f32_e64 s[6:7], 0, v86
	s_nop 1
	v_cndmask_b32_e64 v82, v82, v84, s[6:7]
	v_mul_f32_e32 v83, 0x37800000, v82
	v_cndmask_b32_e32 v82, v82, v83, vcc
	v_cmp_class_f32_e32 vcc, v1, v172
	s_nop 1
	v_cndmask_b32_e32 v1, v82, v1, vcc
	v_div_scale_f32 v82, s[6:7], v1, v1, 1.0
	v_rcp_f32_e32 v83, v82
	v_div_scale_f32 v84, vcc, 1.0, v1, 1.0
	v_fma_f32 v85, -v82, v83, 1.0
	v_fmac_f32_e32 v83, v85, v83
	v_mul_f32_e32 v85, v84, v83
	v_fma_f32 v86, -v82, v85, v84
	v_fmac_f32_e32 v85, v86, v83
	v_fma_f32 v82, -v82, v85, v84
	v_div_fmas_f32 v82, v82, v83, v85
	v_div_fixup_f32 v82, v82, v1, 1.0
	v_pk_mul_f32 v[48:49], v[48:49], v[82:83] op_sel_hi:[1,0]
	v_pk_mul_f32 v[50:51], v[50:51], v[82:83] op_sel_hi:[1,0]
	v_pk_mul_f32 v[44:45], v[44:45], v[82:83] op_sel_hi:[1,0]
	v_pk_mul_f32 v[46:47], v[46:47], v[82:83] op_sel_hi:[1,0]
	v_pk_mul_f32 v[40:41], v[40:41], v[82:83] op_sel_hi:[1,0]
	v_pk_mul_f32 v[42:43], v[42:43], v[82:83] op_sel_hi:[1,0]
	v_pk_mul_f32 v[36:37], v[36:37], v[82:83] op_sel_hi:[1,0]
	v_pk_mul_f32 v[38:39], v[38:39], v[82:83] op_sel_hi:[1,0]
	v_pk_fma_f32 v[50:51], v[138:139], v[50:51], v[68:69]
	v_pk_fma_f32 v[48:49], v[136:137], v[48:49], v[76:77]
	v_pk_fma_f32 v[46:47], v[134:135], v[46:47], v[70:71]
	v_pk_fma_f32 v[44:45], v[132:133], v[44:45], v[78:79]
	v_pk_fma_f32 v[42:43], v[130:131], v[42:43], v[72:73]
	v_pk_fma_f32 v[40:41], v[128:129], v[40:41], v[80:81]
	v_pk_fma_f32 v[68:69], v[122:123], v[38:39], v[74:75]
	v_pk_fma_f32 v[60:61], v[120:121], v[36:37], v[60:61]
	v_cvt_pk_bf16_f32 v36, v48, v49
	v_cvt_pk_bf16_f32 v37, v50, v51
	v_cvt_pk_bf16_f32 v38, v44, v45
	v_cvt_pk_bf16_f32 v39, v46, v47
	v_cvt_pk_bf16_f32 v40, v40, v41
	v_cvt_pk_bf16_f32 v41, v42, v43
	v_cvt_pk_bf16_f32 v42, v60, v61
	v_cvt_pk_bf16_f32 v43, v68, v69
	global_store_dwordx4 v[64:65], v[36:39], off sc1
	global_store_dwordx4 v[64:65], v[40:43], off offset:256 sc1
	global_load_dwordx2 v[44:45], v[66:67], off offset:8
	v_add_u32_e32 v36, 0xb0, v166
	v_ashrrev_i32_e32 v37, 31, v36
	v_lshl_add_u64 v[48:49], s[24:25], 0, v[62:63]
	s_waitcnt vmcnt(4)
	v_lshlrev_b32_e32 v60, 16, v52
	v_and_b32_e32 v61, 0xffff0000, v52
	v_lshlrev_b32_e32 v52, 16, v53
	v_and_b32_e32 v53, 0xffff0000, v53
	v_lshlrev_b32_e32 v62, 16, v54
	v_and_b32_e32 v63, 0xffff0000, v54
	v_lshlrev_b32_e32 v54, 16, v55
	v_and_b32_e32 v55, 0xffff0000, v55
	v_lshlrev_b32_e32 v38, 2, v36
	v_lshlrev_b64 v[46:47], 11, v[36:37]
	s_waitcnt vmcnt(3)
	v_lshlrev_b32_e32 v64, 16, v56
	v_and_b32_e32 v65, 0xffff0000, v56
	v_lshlrev_b32_e32 v56, 16, v57
	v_and_b32_e32 v57, 0xffff0000, v57
	v_ashrrev_i32_e32 v39, 31, v38
	v_lshl_add_u64 v[40:41], v[164:165], 0, v[46:47]
	v_lshl_add_u64 v[48:49], v[48:49], 0, v[2:3]
	v_lshl_add_u64 v[50:51], v[38:39], 2, s[46:47]
	global_load_dwordx4 v[36:39], v[40:41], off
	s_nop 0
	global_load_dwordx4 v[40:43], v[40:41], off offset:256
	s_waitcnt vmcnt(2)
; __device__ __forceinline__ unsigned cvt_pk_bf16(float lo, float hi) { f32x2c_t v = {lo, hi}; bf16x2c_t b = __builtin_convertvector(v, bf16x2c_t); return __builtin_bit_cast(unsigned, b); }
; __device__ __forceinline__ f32x4 bf4_lo(u32x4 w) { return (f32x4){__uint_as_float(w.x << 16), __uint_as_float(w.x & 0xffff0000u), __uint_as_float(w.y << 16), __uint_as_float(w.y & 0xffff0000u)}; }
; __device__ __forceinline__ f32x4 bf4_hi(u32x4 w) { return (f32x4){__uint_as_float(w.z << 16), __uint_as_float(w.z & 0xffff0000u), __uint_as_float(w.w << 16), __uint_as_float(w.w & 0xffff0000u)}; }
;     __device__ __forceinline__ void operator()(const f32x4 (&acc)[2][2][4][2], const Unit& u, int wr, int wc, int fr, int fq) const {
;     ...
;         for (int ai = 0; ai < 2; ++ai)
; #pragma unroll
;             for (int m = 0; m < 4; ++m) { const int row = row0 + ai * HALF + m * 16; const size_t off = (size_t)row * 1024 + col0; float rs = 1.f; if constexpr (MIX) { const float* sp = rs2 + 4 * row + 2; rs = 1.0f / sqrtf((sp[0] + sp[1]) * (1.f / 512.f) + NEPS); }
; #pragma unroll
;                 for (int bj = 0; bj < 2; ++bj) { f32x4 x0, x1;
;                     if constexpr (XF32) { x0 = *(const f32x4*)((const float*)xin + off + bj * HALF); x1 = *(const f32x4*)((const float*)xin + off + bj * HALF + 4); }
;                     else { const u32x4 w = xw[ai][m][bj]; x0 = bf4_lo(w); x1 = bf4_hi(w); }
;                     const f32x4 o0 = x0 + gv[bj][0] * (acc[ai][bj][m][0] * rs), o1 = x1 + gv[bj][1] * (acc[ai][bj][m][1] * rs);
;                     u32x4 w; w.x = cvt_pk_bf16(o0[0], o0[1]); w.y = cvt_pk_bf16(o0[2], o0[3]); w.z = cvt_pk_bf16(o1[0], o1[1]); w.w = cvt_pk_bf16(o1[2], o1[3]);
;                     *(u32x4*)(xout + off + bj * HALF) = w; } }
	v_add_f32_e32 v1, v44, v45
	v_fmamk_f32 v1, v1, 0x3b000000, v174
	v_mul_f32_e32 v44, 0x4f800000, v1
	v_cmp_gt_f32_e32 vcc, s61, v1
	v_and_b32_e32 v45, 0xffff0000, v58
	s_nop 0
	v_cndmask_b32_e32 v1, v1, v44, vcc
	v_sqrt_f32_e32 v66, v1
	v_lshlrev_b32_e32 v44, 16, v58
	v_lshlrev_b32_e32 v58, 16, v59
	v_and_b32_e32 v59, 0xffff0000, v59
	v_add_u32_e32 v67, -1, v66
	v_add_u32_e32 v68, 1, v66
	v_fma_f32 v69, -v67, v66, v1
	v_fma_f32 v70, -v68, v66, v1
	v_cmp_ge_f32_e64 s[6:7], 0, v69
	s_nop 1
	v_cndmask_b32_e64 v66, v66, v67, s[6:7]
	v_cmp_lt_f32_e64 s[6:7], 0, v70
	s_nop 1
	v_cndmask_b32_e64 v66, v66, v68, s[6:7]
	v_mul_f32_e32 v67, 0x37800000, v66
	v_cndmask_b32_e32 v66, v66, v67, vcc
	v_cmp_class_f32_e32 vcc, v1, v172
	s_nop 1
	v_cndmask_b32_e32 v1, v66, v1, vcc
	v_div_scale_f32 v66, s[6:7], v1, v1, 1.0
	v_rcp_f32_e32 v67, v66
	v_div_scale_f32 v68, vcc, 1.0, v1, 1.0
	v_fma_f32 v69, -v66, v67, 1.0
	v_fmac_f32_e32 v67, v69, v67
	v_mul_f32_e32 v69, v68, v67
	v_fma_f32 v70, -v66, v69, v68
	v_fmac_f32_e32 v69, v70, v67
	v_fma_f32 v66, -v66, v69, v68
	v_div_fmas_f32 v66, v66, v67, v69
	v_div_fixup_f32 v66, v66, v1, 1.0
	v_pk_mul_f32 v[32:33], v[32:33], v[66:67] op_sel_hi:[1,0]
	v_pk_mul_f32 v[34:35], v[34:35], v[66:67] op_sel_hi:[1,0]
	v_pk_mul_f32 v[28:29], v[28:29], v[66:67] op_sel_hi:[1,0]
	v_pk_mul_f32 v[30:31], v[30:31], v[66:67] op_sel_hi:[1,0]
	v_pk_mul_f32 v[24:25], v[24:25], v[66:67] op_sel_hi:[1,0]
	v_pk_mul_f32 v[26:27], v[26:27], v[66:67] op_sel_hi:[1,0]
	v_pk_mul_f32 v[20:21], v[20:21], v[66:67] op_sel_hi:[1,0]
	v_pk_mul_f32 v[22:23], v[22:23], v[66:67] op_sel_hi:[1,0]
	v_pk_fma_f32 v[34:35], v[138:139], v[34:35], v[52:53]
	v_pk_fma_f32 v[32:33], v[136:137], v[32:33], v[60:61]
	v_pk_fma_f32 v[30:31], v[134:135], v[30:31], v[54:55]
	v_pk_fma_f32 v[28:29], v[132:133], v[28:29], v[62:63]
	v_pk_fma_f32 v[26:27], v[130:131], v[26:27], v[56:57]
	v_pk_fma_f32 v[24:25], v[128:129], v[24:25], v[64:65]
	v_pk_fma_f32 v[52:53], v[122:123], v[22:23], v[58:59]
	v_pk_fma_f32 v[44:45], v[120:121], v[20:21], v[44:45]
	v_cvt_pk_bf16_f32 v20, v32, v33
	v_cvt_pk_bf16_f32 v21, v34, v35
	v_cvt_pk_bf16_f32 v22, v28, v29
	v_cvt_pk_bf16_f32 v23, v30, v31
	v_cvt_pk_bf16_f32 v24, v24, v25
	v_cvt_pk_bf16_f32 v25, v26, v27
	v_cvt_pk_bf16_f32 v26, v44, v45
	v_cvt_pk_bf16_f32 v27, v52, v53
	global_store_dwordx4 v[48:49], v[20:23], off sc1
	global_store_dwordx4 v[48:49], v[24:27], off offset:256 sc1
	global_load_dwordx2 v[20:21], v[50:51], off offset:8
	v_lshl_add_u64 v[22:23], s[24:25], 0, v[46:47]
	v_lshl_add_u64 v[22:23], v[22:23], 0, v[2:3]
	s_waitcnt vmcnt(4)
	v_lshlrev_b32_e32 v2, 16, v36
	v_and_b32_e32 v3, 0xffff0000, v36
	v_lshlrev_b32_e32 v24, 16, v37
	v_and_b32_e32 v25, 0xffff0000, v37
	v_lshlrev_b32_e32 v26, 16, v38
	v_and_b32_e32 v27, 0xffff0000, v38
	v_lshlrev_b32_e32 v28, 16, v39
	v_and_b32_e32 v29, 0xffff0000, v39
	s_waitcnt vmcnt(3)
	v_lshlrev_b32_e32 v30, 16, v40
	v_and_b32_e32 v31, 0xffff0000, v40
	v_lshlrev_b32_e32 v32, 16, v41
	v_and_b32_e32 v33, 0xffff0000, v41
	v_lshlrev_b32_e32 v34, 16, v43
	s_waitcnt vmcnt(0)
	v_add_f32_e32 v1, v20, v21
	v_fmamk_f32 v1, v1, 0x3b000000, v174
	v_mul_f32_e32 v20, 0x4f800000, v1
	v_cmp_gt_f32_e32 vcc, s61, v1
	v_and_b32_e32 v21, 0xffff0000, v42
	s_nop 0
	v_cndmask_b32_e32 v1, v1, v20, vcc
	v_sqrt_f32_e32 v35, v1
	v_lshlrev_b32_e32 v20, 16, v42
	v_add_u32_e32 v36, -1, v35
	v_add_u32_e32 v37, 1, v35
	v_fma_f32 v38, -v36, v35, v1
	v_fma_f32 v39, -v37, v35, v1
	v_cmp_ge_f32_e64 s[6:7], 0, v38
	s_nop 1
	v_cndmask_b32_e64 v35, v35, v36, s[6:7]
	v_cmp_lt_f32_e64 s[6:7], 0, v39
	s_nop 1
	v_cndmask_b32_e64 v35, v35, v37, s[6:7]
	v_mul_f32_e32 v36, 0x37800000, v35
	v_cndmask_b32_e32 v35, v35, v36, vcc
	v_cmp_class_f32_e32 vcc, v1, v172
	s_nop 1
	v_cndmask_b32_e32 v1, v35, v1, vcc
	v_div_scale_f32 v36, s[6:7], v1, v1, 1.0
	v_rcp_f32_e32 v37, v36
	v_div_scale_f32 v38, vcc, 1.0, v1, 1.0
	v_and_b32_e32 v35, 0xffff0000, v43
	v_fma_f32 v39, -v36, v37, 1.0
	v_fmac_f32_e32 v37, v39, v37
	v_mul_f32_e32 v39, v38, v37
	v_fma_f32 v40, -v36, v39, v38
	v_fmac_f32_e32 v39, v40, v37
	v_fma_f32 v36, -v36, v39, v38
	v_div_fmas_f32 v36, v36, v37, v39
	v_div_fixup_f32 v36, v36, v1, 1.0
	v_pk_mul_f32 v[16:17], v[16:17], v[36:37] op_sel_hi:[1,0]
	v_pk_mul_f32 v[18:19], v[18:19], v[36:37] op_sel_hi:[1,0]
	v_pk_mul_f32 v[12:13], v[12:13], v[36:37] op_sel_hi:[1,0]
	v_pk_mul_f32 v[14:15], v[14:15], v[36:37] op_sel_hi:[1,0]
	v_pk_mul_f32 v[8:9], v[8:9], v[36:37] op_sel_hi:[1,0]
	v_pk_mul_f32 v[10:11], v[10:11], v[36:37] op_sel_hi:[1,0]
	v_pk_mul_f32 v[4:5], v[4:5], v[36:37] op_sel_hi:[1,0]
	v_pk_mul_f32 v[6:7], v[6:7], v[36:37] op_sel_hi:[1,0]
	v_pk_fma_f32 v[18:19], v[138:139], v[18:19], v[24:25]
	v_pk_fma_f32 v[2:3], v[136:137], v[16:17], v[2:3]
	v_pk_fma_f32 v[14:15], v[134:135], v[14:15], v[28:29]
	v_pk_fma_f32 v[12:13], v[132:133], v[12:13], v[26:27]
	s_andn2_b64 vcc, exec, s[0:1]
	v_pk_fma_f32 v[10:11], v[130:131], v[10:11], v[32:33]
	v_pk_fma_f32 v[8:9], v[128:129], v[8:9], v[30:31]
	v_pk_fma_f32 v[16:17], v[122:123], v[6:7], v[34:35]
	v_pk_fma_f32 v[20:21], v[120:121], v[4:5], v[20:21]
	v_cvt_pk_bf16_f32 v2, v2, v3
	v_cvt_pk_bf16_f32 v3, v18, v19
	v_cvt_pk_bf16_f32 v4, v12, v13
	v_cvt_pk_bf16_f32 v5, v14, v15
	s_mov_b64 s[0:1], -1
	v_cvt_pk_bf16_f32 v6, v8, v9
	v_cvt_pk_bf16_f32 v7, v10, v11
	v_cvt_pk_bf16_f32 v8, v20, v21
	v_cvt_pk_bf16_f32 v9, v16, v17
	global_store_dwordx4 v[22:23], v[2:5], off sc1
	global_store_dwordx4 v[22:23], v[6:9], off offset:256 sc1
	s_cbranch_vccnz .LBB0_890
	s_andn2_b64 vcc, exec, s[16:17]
	s_cbranch_vccnz .LBB0_889
	s_barrier
	s_branch .LBB0_889

; __device__ __forceinline__ unsigned cvt_pk_bf16(float lo, float hi) { f32x2c_t v = {lo, hi}; bf16x2c_t b = __builtin_convertvector(v, bf16x2c_t); return __builtin_bit_cast(unsigned, b); }
; __device__ __forceinline__ unsigned swi2(float a0, float a1, float b0, float b1) {
;     const f32x2s a = {a0, a1}, b = {b0, b1};
;     f32x2s e; e.x = __builtin_amdgcn_exp2f(-a.x); e.y = __builtin_amdgcn_exp2f(-a.y);
;     const f32x2s d = e + 1.0f; f32x2s r; r.x = __builtin_amdgcn_rcpf(d.x); r.y = __builtin_amdgcn_rcpf(d.y);
;     const f32x2s o = (a * b) * r;
;     return cvt_pk_bf16(o.x, o.y);
; }
;     __device__ __forceinline__ void operator()(const f32x4 (&acc)[2][2][4][2], const Unit& u, int wr, int wc, int fr, int fq) const {
;     ...
;         for (int ai = 0; ai < 2; ++ai)
; #pragma unroll
;             for (int m = 0; m < 4; ++m) {
;                 bf16_t* rowp = O + (size_t)(row0 + ai * HALF + m * 16) * 2816 + col0;
;                 const f32x4 a0 = acc[ai][0][m][0], a1 = acc[ai][0][m][1], b0 = acc[ai][1][m][0], b1 = acc[ai][1][m][1];
;                 u32x4 w;
;                 w.x = swi2(a0[0], a0[1], b0[0], b0[1]); w.y = swi2(a0[2], a0[3], b0[2], b0[3]);
;                 w.z = swi2(a1[0], a1[1], b1[0], b1[1]); w.w = swi2(a1[2], a1[3], b1[2], b1[3]);
.LBB0_1028:
	v_exp_f32_e64 v158, -v126
	v_exp_f32_e64 v159, -v127
	v_exp_f32_e64 v154, -v124
	v_exp_f32_e64 v155, -v125
	v_pk_mul_f32 v[120:121], v[124:125], v[120:121]
	v_pk_add_f32 v[124:125], v[158:159], 1.0 op_sel_hi:[1,0]
	v_pk_mul_f32 v[122:123], v[126:127], v[122:123]
	v_rcp_f32_e32 v124, v124
	v_rcp_f32_e32 v125, v125
	v_pk_add_f32 v[154:155], v[154:155], 1.0 op_sel_hi:[1,0]
	v_exp_f32_e64 v126, -v116
	v_rcp_f32_e32 v154, v154
	v_rcp_f32_e32 v155, v155
	v_exp_f32_e64 v127, -v117
	v_pk_mul_f32 v[122:123], v[124:125], v[122:123]
	v_exp_f32_e64 v124, -v118
	v_exp_f32_e64 v125, -v119
	v_pk_mul_f32 v[120:121], v[154:155], v[120:121]
	v_pk_mul_f32 v[114:115], v[118:119], v[114:115]
	v_cvt_pk_bf16_f32 v120, v120, v121
	v_cvt_pk_bf16_f32 v121, v122, v123
	v_pk_add_f32 v[122:123], v[126:127], 1.0 op_sel_hi:[1,0]
	v_pk_add_f32 v[118:119], v[124:125], 1.0 op_sel_hi:[1,0]
	v_rcp_f32_e32 v122, v122
	v_rcp_f32_e32 v123, v123
	v_rcp_f32_e32 v118, v118
	v_rcp_f32_e32 v119, v119
	v_pk_mul_f32 v[112:113], v[116:117], v[112:113]
	v_exp_f32_e64 v116, -v110
	v_pk_mul_f32 v[112:113], v[122:123], v[112:113]
	v_exp_f32_e64 v117, -v111
	v_cvt_pk_bf16_f32 v122, v112, v113
	v_pk_mul_f32 v[112:113], v[118:119], v[114:115]
	v_pk_mul_f32 v[104:105], v[108:109], v[104:105]
	v_cvt_pk_bf16_f32 v123, v112, v113
	v_exp_f32_e64 v112, -v108
	v_exp_f32_e64 v113, -v109
	v_pk_add_f32 v[108:109], v[116:117], 1.0 op_sel_hi:[1,0]
	v_pk_mul_f32 v[106:107], v[110:111], v[106:107]
	v_rcp_f32_e32 v108, v108
	v_rcp_f32_e32 v109, v109
	v_pk_add_f32 v[112:113], v[112:113], 1.0 op_sel_hi:[1,0]
	v_exp_f32_e64 v110, -v100
	v_rcp_f32_e32 v112, v112
	v_rcp_f32_e32 v113, v113
	v_exp_f32_e64 v111, -v101
	v_pk_mul_f32 v[106:107], v[108:109], v[106:107]
	v_exp_f32_e64 v108, -v102
	v_exp_f32_e64 v109, -v103
	v_pk_mul_f32 v[104:105], v[112:113], v[104:105]
	v_pk_mul_f32 v[98:99], v[102:103], v[98:99]
	v_cvt_pk_bf16_f32 v104, v104, v105
	v_cvt_pk_bf16_f32 v105, v106, v107
	v_pk_add_f32 v[106:107], v[110:111], 1.0 op_sel_hi:[1,0]
	v_pk_add_f32 v[102:103], v[108:109], 1.0 op_sel_hi:[1,0]
	v_rcp_f32_e32 v106, v106
	v_rcp_f32_e32 v107, v107
	v_rcp_f32_e32 v102, v102
	v_rcp_f32_e32 v103, v103
	v_pk_mul_f32 v[96:97], v[100:101], v[96:97]
	v_exp_f32_e64 v100, -v94
	v_pk_mul_f32 v[96:97], v[106:107], v[96:97]
	v_exp_f32_e64 v101, -v95
	v_cvt_pk_bf16_f32 v106, v96, v97
	v_pk_mul_f32 v[96:97], v[102:103], v[98:99]
	v_pk_mul_f32 v[88:89], v[92:93], v[88:89]
	v_cvt_pk_bf16_f32 v107, v96, v97
	v_exp_f32_e64 v96, -v92
	v_exp_f32_e64 v97, -v93
	v_pk_add_f32 v[92:93], v[100:101], 1.0 op_sel_hi:[1,0]
	v_pk_mul_f32 v[90:91], v[94:95], v[90:91]
	v_rcp_f32_e32 v92, v92
	v_rcp_f32_e32 v93, v93
	v_pk_add_f32 v[96:97], v[96:97], 1.0 op_sel_hi:[1,0]
	v_exp_f32_e64 v94, -v84
	v_rcp_f32_e32 v96, v96
	v_rcp_f32_e32 v97, v97
	v_exp_f32_e64 v95, -v85
	v_pk_mul_f32 v[90:91], v[92:93], v[90:91]
	v_exp_f32_e64 v92, -v86
	v_exp_f32_e64 v93, -v87
	v_pk_mul_f32 v[88:89], v[96:97], v[88:89]
	v_pk_mul_f32 v[82:83], v[86:87], v[82:83]
	v_cvt_pk_bf16_f32 v88, v88, v89
	v_cvt_pk_bf16_f32 v89, v90, v91
	v_pk_add_f32 v[90:91], v[94:95], 1.0 op_sel_hi:[1,0]
	v_pk_add_f32 v[86:87], v[92:93], 1.0 op_sel_hi:[1,0]
	v_rcp_f32_e32 v90, v90
	v_rcp_f32_e32 v91, v91
	v_rcp_f32_e32 v86, v86
	v_rcp_f32_e32 v87, v87
	v_pk_mul_f32 v[80:81], v[84:85], v[80:81]
	v_exp_f32_e64 v84, -v78
	v_pk_mul_f32 v[80:81], v[90:91], v[80:81]
	v_exp_f32_e64 v85, -v79
	v_cvt_pk_bf16_f32 v90, v80, v81
	v_pk_mul_f32 v[80:81], v[86:87], v[82:83]
	v_pk_mul_f32 v[72:73], v[76:77], v[72:73]
	v_cvt_pk_bf16_f32 v91, v80, v81
	v_exp_f32_e64 v80, -v76
	v_exp_f32_e64 v81, -v77
	v_pk_add_f32 v[76:77], v[84:85], 1.0 op_sel_hi:[1,0]
	v_pk_mul_f32 v[74:75], v[78:79], v[74:75]
	v_rcp_f32_e32 v76, v76
	v_rcp_f32_e32 v77, v77
	v_pk_add_f32 v[80:81], v[80:81], 1.0 op_sel_hi:[1,0]
	v_exp_f32_e64 v78, -v68
	v_rcp_f32_e32 v80, v80
	v_rcp_f32_e32 v81, v81
	v_exp_f32_e64 v79, -v69
	v_pk_mul_f32 v[74:75], v[76:77], v[74:75]
	v_exp_f32_e64 v76, -v70
	v_exp_f32_e64 v77, -v71
	v_pk_mul_f32 v[72:73], v[80:81], v[72:73]
	v_pk_mul_f32 v[66:67], v[70:71], v[66:67]
	v_cvt_pk_bf16_f32 v72, v72, v73
	v_cvt_pk_bf16_f32 v73, v74, v75
	v_pk_add_f32 v[74:75], v[78:79], 1.0 op_sel_hi:[1,0]
	v_pk_add_f32 v[70:71], v[76:77], 1.0 op_sel_hi:[1,0]
	v_rcp_f32_e32 v74, v74
	v_rcp_f32_e32 v75, v75
	v_rcp_f32_e32 v70, v70
	v_rcp_f32_e32 v71, v71
	v_pk_mul_f32 v[64:65], v[68:69], v[64:65]
	v_exp_f32_e64 v68, -v62
	v_pk_mul_f32 v[64:65], v[74:75], v[64:65]
	v_exp_f32_e64 v69, -v63
	v_cvt_pk_bf16_f32 v74, v64, v65
	v_pk_mul_f32 v[64:65], v[70:71], v[66:67]
	v_pk_mul_f32 v[56:57], v[60:61], v[56:57]
	v_cvt_pk_bf16_f32 v75, v64, v65
	v_exp_f32_e64 v64, -v60
	v_exp_f32_e64 v65, -v61
	v_pk_add_f32 v[60:61], v[68:69], 1.0 op_sel_hi:[1,0]
	v_pk_mul_f32 v[58:59], v[62:63], v[58:59]
	v_rcp_f32_e32 v60, v60
	v_rcp_f32_e32 v61, v61
	v_pk_add_f32 v[64:65], v[64:65], 1.0 op_sel_hi:[1,0]
	v_exp_f32_e64 v62, -v52
	v_rcp_f32_e32 v64, v64
	v_rcp_f32_e32 v65, v65
	v_exp_f32_e64 v63, -v53
	v_pk_mul_f32 v[58:59], v[60:61], v[58:59]
	v_exp_f32_e64 v60, -v54
	v_exp_f32_e64 v61, -v55
	v_pk_mul_f32 v[56:57], v[64:65], v[56:57]
	v_pk_mul_f32 v[50:51], v[54:55], v[50:51]
	v_cvt_pk_bf16_f32 v56, v56, v57
; __device__ __forceinline__ unsigned cvt_pk_bf16(float lo, float hi) { f32x2c_t v = {lo, hi}; bf16x2c_t b = __builtin_convertvector(v, bf16x2c_t); return __builtin_bit_cast(unsigned, b); }
; __device__ __forceinline__ unsigned swi2(float a0, float a1, float b0, float b1) {
;     const f32x2s a = {a0, a1}, b = {b0, b1};
;     f32x2s e; e.x = __builtin_amdgcn_exp2f(-a.x); e.y = __builtin_amdgcn_exp2f(-a.y);
;     const f32x2s d = e + 1.0f; f32x2s r; r.x = __builtin_amdgcn_rcpf(d.x); r.y = __builtin_amdgcn_rcpf(d.y);
;     const f32x2s o = (a * b) * r;
;     return cvt_pk_bf16(o.x, o.y);
;     __device__ __forceinline__ void operator()(const f32x4 (&acc)[2][2][4][2], const Unit& u, int wr, int wc, int fr, int fq) const {
;     ...
;         const int row0 = u.pm * BM + wr * 64 + fr, col0 = u.pn * 128 + wc * 32 + 8 * fq;
; #pragma unroll
;         for (int ai = 0; ai < 2; ++ai)
; #pragma unroll
;             for (int m = 0; m < 4; ++m) {
;                 bf16_t* rowp = O + (size_t)(row0 + ai * HALF + m * 16) * 2816 + col0;
;                 const f32x4 a0 = acc[ai][0][m][0], a1 = acc[ai][0][m][1], b0 = acc[ai][1][m][0], b1 = acc[ai][1][m][1];
;                 u32x4 w;
;                 w.x = swi2(a0[0], a0[1], b0[0], b0[1]); w.y = swi2(a0[2], a0[3], b0[2], b0[3]);
;                 w.z = swi2(a1[0], a1[1], b1[0], b1[1]); w.w = swi2(a1[2], a1[3], b1[2], b1[3]);
;                 *(u32x4*)rowp = w;
	v_cvt_pk_bf16_f32 v57, v58, v59
	v_pk_add_f32 v[58:59], v[62:63], 1.0 op_sel_hi:[1,0]
	v_pk_add_f32 v[54:55], v[60:61], 1.0 op_sel_hi:[1,0]
	v_rcp_f32_e32 v58, v58
	v_rcp_f32_e32 v59, v59
	v_rcp_f32_e32 v54, v54
	v_rcp_f32_e32 v55, v55
	v_pk_mul_f32 v[48:49], v[52:53], v[48:49]
	v_exp_f32_e64 v52, -v46
	v_pk_mul_f32 v[48:49], v[58:59], v[48:49]
	v_exp_f32_e64 v53, -v47
	v_cvt_pk_bf16_f32 v58, v48, v49
	v_pk_mul_f32 v[48:49], v[54:55], v[50:51]
	v_pk_mul_f32 v[40:41], v[44:45], v[40:41]
	v_cvt_pk_bf16_f32 v59, v48, v49
	v_exp_f32_e64 v48, -v44
	v_exp_f32_e64 v49, -v45
	v_pk_add_f32 v[44:45], v[52:53], 1.0 op_sel_hi:[1,0]
	v_pk_mul_f32 v[42:43], v[46:47], v[42:43]
	v_rcp_f32_e32 v44, v44
	v_rcp_f32_e32 v45, v45
	v_pk_add_f32 v[48:49], v[48:49], 1.0 op_sel_hi:[1,0]
	v_exp_f32_e64 v46, -v36
	v_rcp_f32_e32 v48, v48
	v_rcp_f32_e32 v49, v49
	v_exp_f32_e64 v47, -v37
	v_pk_mul_f32 v[42:43], v[44:45], v[42:43]
	v_exp_f32_e64 v44, -v38
	v_exp_f32_e64 v45, -v39
	v_pk_mul_f32 v[40:41], v[48:49], v[40:41]
	v_pk_mul_f32 v[34:35], v[38:39], v[34:35]
	v_cvt_pk_bf16_f32 v40, v40, v41
	v_cvt_pk_bf16_f32 v41, v42, v43
	v_pk_add_f32 v[42:43], v[46:47], 1.0 op_sel_hi:[1,0]
	v_pk_add_f32 v[38:39], v[44:45], 1.0 op_sel_hi:[1,0]
	v_rcp_f32_e32 v42, v42
	v_rcp_f32_e32 v43, v43
	v_rcp_f32_e32 v38, v38
	v_rcp_f32_e32 v39, v39
	v_pk_mul_f32 v[32:33], v[36:37], v[32:33]
	v_exp_f32_e64 v36, -v30
	v_pk_mul_f32 v[32:33], v[42:43], v[32:33]
	v_exp_f32_e64 v37, -v31
	v_cvt_pk_bf16_f32 v42, v32, v33
	v_pk_mul_f32 v[32:33], v[38:39], v[34:35]
	v_pk_mul_f32 v[24:25], v[28:29], v[24:25]
	v_cvt_pk_bf16_f32 v43, v32, v33
	v_exp_f32_e64 v32, -v28
	v_exp_f32_e64 v33, -v29
	v_pk_add_f32 v[28:29], v[36:37], 1.0 op_sel_hi:[1,0]
	v_pk_mul_f32 v[26:27], v[30:31], v[26:27]
	v_rcp_f32_e32 v28, v28
	v_rcp_f32_e32 v29, v29
	v_pk_add_f32 v[32:33], v[32:33], 1.0 op_sel_hi:[1,0]
	v_exp_f32_e64 v30, -v20
	v_rcp_f32_e32 v32, v32
	v_rcp_f32_e32 v33, v33
	v_exp_f32_e64 v31, -v21
	v_pk_mul_f32 v[26:27], v[28:29], v[26:27]
	v_exp_f32_e64 v28, -v22
	v_exp_f32_e64 v29, -v23
	v_pk_mul_f32 v[24:25], v[32:33], v[24:25]
	v_pk_mul_f32 v[18:19], v[22:23], v[18:19]
	v_cvt_pk_bf16_f32 v24, v24, v25
	v_cvt_pk_bf16_f32 v25, v26, v27
	v_pk_add_f32 v[26:27], v[30:31], 1.0 op_sel_hi:[1,0]
	v_pk_add_f32 v[22:23], v[28:29], 1.0 op_sel_hi:[1,0]
	v_rcp_f32_e32 v26, v26
	v_rcp_f32_e32 v27, v27
	v_rcp_f32_e32 v22, v22
	v_rcp_f32_e32 v23, v23
	v_pk_mul_f32 v[16:17], v[20:21], v[16:17]
	v_exp_f32_e64 v20, -v14
	v_pk_mul_f32 v[16:17], v[26:27], v[16:17]
	v_exp_f32_e64 v21, -v15
	v_cvt_pk_bf16_f32 v26, v16, v17
	v_pk_mul_f32 v[16:17], v[22:23], v[18:19]
	v_pk_mul_f32 v[8:9], v[12:13], v[8:9]
	v_cvt_pk_bf16_f32 v27, v16, v17
	v_exp_f32_e64 v16, -v12
	v_exp_f32_e64 v17, -v13
	v_pk_add_f32 v[12:13], v[20:21], 1.0 op_sel_hi:[1,0]
	v_pk_mul_f32 v[10:11], v[14:15], v[10:11]
	v_rcp_f32_e32 v12, v12
	v_rcp_f32_e32 v13, v13
	v_pk_add_f32 v[16:17], v[16:17], 1.0 op_sel_hi:[1,0]
	v_exp_f32_e64 v14, -v4
	v_rcp_f32_e32 v16, v16
	v_rcp_f32_e32 v17, v17
	v_exp_f32_e64 v15, -v5
	v_pk_mul_f32 v[10:11], v[12:13], v[10:11]
	v_exp_f32_e64 v12, -v6
	v_exp_f32_e64 v13, -v7
	v_pk_mul_f32 v[8:9], v[16:17], v[8:9]
	v_pk_mul_f32 v[2:3], v[6:7], v[2:3]
	v_cvt_pk_bf16_f32 v8, v8, v9
	v_cvt_pk_bf16_f32 v9, v10, v11
	v_pk_add_f32 v[10:11], v[14:15], 1.0 op_sel_hi:[1,0]
	v_pk_add_f32 v[6:7], v[12:13], 1.0 op_sel_hi:[1,0]
	v_rcp_f32_e32 v10, v10
	v_rcp_f32_e32 v11, v11
	v_mov_b32_e32 v145, v146
	v_mov_b32_e32 v144, v147
	s_lshl_b32 s19, s58, 7
	v_rcp_f32_e32 v6, v6
	v_rcp_f32_e32 v7, v7
	s_lshl_b32 s17, s38, 8
	s_or_b32 s19, s19, s48
	v_lshl_add_u32 v144, v144, 3, s19
	s_add_i32 s17, s17, s47
	v_pk_mul_f32 v[0:1], v[4:5], v[0:1]
	v_add_u32_e32 v152, s17, v145
	v_ashrrev_i32_e32 v145, 31, v144
	v_pk_mul_f32 v[0:1], v[10:11], v[0:1]
	v_lshl_add_u64 v[144:145], v[144:145], 1, s[22:23]
	v_add_u32_e32 v114, 16, v152
	v_add_u32_e32 v98, 32, v152
	v_add_u32_e32 v82, 48, v152
	v_add_u32_e32 v66, 0x80, v152
	v_add_u32_e32 v50, 0x90, v152
	v_add_u32_e32 v34, 0xa0, v152
	v_add_u32_e32 v18, 0xb0, v152
	v_cvt_pk_bf16_f32 v10, v0, v1
	v_pk_mul_f32 v[0:1], v[6:7], v[2:3]
	v_mad_i64_i32 v[156:157], s[40:41], v152, s55, v[144:145]
	v_mad_i64_i32 v[114:115], s[40:41], v114, s55, v[144:145]
	v_mad_i64_i32 v[98:99], s[40:41], v98, s55, v[144:145]
	v_mad_i64_i32 v[82:83], s[40:41], v82, s55, v[144:145]
	v_mad_i64_i32 v[66:67], s[40:41], v66, s55, v[144:145]
	v_mad_i64_i32 v[50:51], s[40:41], v50, s55, v[144:145]
	v_mad_i64_i32 v[34:35], s[40:41], v34, s55, v[144:145]
	v_mad_i64_i32 v[18:19], s[40:41], v18, s55, v[144:145]
	v_cvt_pk_bf16_f32 v11, v0, v1
	s_andn2_b64 vcc, exec, s[0:1]
	s_mov_b64 s[0:1], -1
	global_store_dwordx4 v[156:157], v[120:123], off sc1
	global_store_dwordx4 v[114:115], v[104:107], off sc1
	global_store_dwordx4 v[98:99], v[88:91], off sc1
	global_store_dwordx4 v[82:83], v[72:75], off sc1
	global_store_dwordx4 v[66:67], v[56:59], off sc1
	global_store_dwordx4 v[50:51], v[40:43], off sc1
	global_store_dwordx4 v[34:35], v[24:27], off sc1
	global_store_dwordx4 v[18:19], v[8:11], off sc1
	s_cbranch_vccnz .LBB0_1021
	s_andn2_b64 vcc, exec, s[6:7]
	s_cbranch_vccnz .LBB0_1020
	s_barrier
	s_branch .LBB0_1020

; __device__ __forceinline__ unsigned cvt_pk_bf16(float lo, float hi) { f32x2c_t v = {lo, hi}; bf16x2c_t b = __builtin_convertvector(v, bf16x2c_t); return __builtin_bit_cast(unsigned, b); }
; __device__ __forceinline__ f32x4 bf4_lo(u32x4 w) { return (f32x4){__uint_as_float(w.x << 16), __uint_as_float(w.x & 0xffff0000u), __uint_as_float(w.y << 16), __uint_as_float(w.y & 0xffff0000u)}; }
;     __device__ __forceinline__ void operator()(const f32x4 (&acc)[2][2][4][2], const Unit& u, int wr, int wc, int fr, int fq) const {
;     ...
;         const int row0 = u.pm * BM + wr * 64 + fr, col0 = u.pn * BM + wc * 32 + 8 * fq, b = u.pm >> 4;
;         f32x4 gv[2][2];
; #pragma unroll
;         for (int bj = 0; bj < 2; ++bj)
; #pragma unroll
;             for (int n = 0; n < 2; ++n) gv[bj][n] = *(const f32x4*)(gate + (size_t)b * NMODC + col0 + bj * HALF + n * 4) * (MIX ? 1.0f : 0.5f);
;         u32x4 xw[2][4][2];
;         if constexpr (!XF32) {
; #pragma unroll
;             for (int ai = 0; ai < 2; ++ai)
; #pragma unroll
;                 for (int m = 0; m < 4; ++m)
; #pragma unroll
;                     for (int bj = 0; bj < 2; ++bj) xw[ai][m][bj] = *(const u32x4*)((const bf16_t*)xin + (size_t)(row0 + ai * HALF + m * 16) * 1024 + col0 + bj * HALF);
;         }
; #pragma unroll
;         for (int ai = 0; ai < 2; ++ai)
; #pragma unroll
;             for (int m = 0; m < 4; ++m) { const int row = row0 + ai * HALF + m * 16; const size_t off = (size_t)row * 1024 + col0; float rs = 1.f; if constexpr (MIX) { const float* sp = rs2 + 4 * row + 2; rs = 1.0f / sqrtf((sp[0] + sp[1]) * (1.f / 512.f) + NEPS); }
; #pragma unroll
;                 for (int bj = 0; bj < 2; ++bj) { f32x4 x0, x1;
;                     if constexpr (XF32) { x0 = *(const f32x4*)((const float*)xin + off + bj * HALF); x1 = *(const f32x4*)((const float*)xin + off + bj * HALF + 4); }
;                     else { const u32x4 w = xw[ai][m][bj]; x0 = bf4_lo(w); x1 = bf4_hi(w); }
;                     const f32x4 o0 = x0 + gv[bj][0] * (acc[ai][bj][m][0] * rs), o1 = x1 + gv[bj][1] * (acc[ai][bj][m][1] * rs);
;                     u32x4 w; w.x = cvt_pk_bf16(o0[0], o0[1]); w.y = cvt_pk_bf16(o0[2], o0[3]); w.z = cvt_pk_bf16(o1[0], o1[1]); w.w = cvt_pk_bf16(o1[2], o1[3]);
;                     *(u32x4*)(xout + off + bj * HALF) = w; } }
.LBB0_1108:
	s_lshl_b32 s46, s67, 8
	s_add_i32 s48, s46, s57
	s_lshl_b32 s46, s68, 8
	v_mov_b32_e32 v128, v239
	v_mov_b32_e32 v140, v238
	s_or_b32 s46, s46, s58
	s_nop 0
	v_lshl_add_u32 v136, v128, 3, s46
	s_ashr_i32 s46, s67, 4
	s_mul_hi_i32 s47, s46, 0x9000
	s_mul_i32 s46, s46, 0x9000
	s_add_u32 s46, s55, s46
	s_addc_u32 s47, s56, s47
	v_ashrrev_i32_e32 v137, 31, v136
	v_lshl_add_u64 v[138:139], v[136:137], 2, s[46:47]
	global_load_dwordx4 v[128:131], v[138:139], off offset:16
	global_load_dwordx4 v[132:135], v[138:139], off
	v_lshlrev_b64 v[222:223], 1, v[136:137]
	s_mov_b64 s[46:47], -1
	s_and_b64 vcc, exec, s[0:1]
	s_waitcnt vmcnt(0)
	v_pk_mul_f32 v[216:217], v[130:131], 0.5 op_sel_hi:[1,0]
	v_pk_mul_f32 v[220:221], v[134:135], 0.5 op_sel_hi:[1,0]
	v_pk_mul_f32 v[218:219], v[132:133], 0.5 op_sel_hi:[1,0]
	v_pk_mul_f32 v[214:215], v[128:129], 0.5 op_sel_hi:[1,0]
	global_load_dwordx4 v[128:131], v[138:139], off offset:528
	global_load_dwordx4 v[132:135], v[138:139], off offset:512
	s_waitcnt vmcnt(1)
	v_pk_mul_f32 v[206:207], v[128:129], 0.5 op_sel_hi:[1,0]
	v_add_u32_e32 v128, s48, v140
	v_ashrrev_i32_e32 v129, 31, v128
	v_pk_mul_f32 v[208:209], v[130:131], 0.5 op_sel_hi:[1,0]
	v_lshl_add_u64 v[130:131], s[24:25], 0, v[222:223]
	v_lshlrev_b64 v[248:249], 11, v[128:129]
	v_lshl_add_u64 v[128:129], v[130:131], 0, v[248:249]
	global_load_dwordx4 v[244:247], v[128:129], off
	global_load_dwordx4 v[184:187], v[128:129], off offset:256
	v_lshl_add_u64 v[236:237], v[248:249], 0, s[14:15]
	v_lshl_add_u64 v[128:129], v[130:131], 0, v[236:237]
	global_load_dwordx4 v[180:183], v[128:129], off
	global_load_dwordx4 v[176:179], v[128:129], off offset:256
	v_lshl_add_u64 v[234:235], v[248:249], 0, s[18:19]
	v_lshl_add_u64 v[128:129], v[130:131], 0, v[234:235]
	global_load_dwordx4 v[172:175], v[128:129], off
	global_load_dwordx4 v[168:171], v[128:129], off offset:256
	v_lshl_add_u64 v[232:233], v[248:249], 0, s[20:21]
	v_lshl_add_u64 v[128:129], v[130:131], 0, v[232:233]
	global_load_dwordx4 v[164:167], v[128:129], off
	global_load_dwordx4 v[160:163], v[128:129], off offset:256
	v_lshl_add_u64 v[230:231], v[248:249], 0, s[36:37]
	v_lshl_add_u64 v[128:129], v[130:131], 0, v[230:231]
	global_load_dwordx4 v[156:159], v[128:129], off
	global_load_dwordx4 v[152:155], v[128:129], off offset:256
	v_lshl_add_u64 v[228:229], v[248:249], 0, s[38:39]
	v_lshl_add_u64 v[128:129], v[130:131], 0, v[228:229]
	global_load_dwordx4 v[148:151], v[128:129], off
	global_load_dwordx4 v[144:147], v[128:129], off offset:256
	v_lshl_add_u64 v[226:227], v[248:249], 0, s[40:41]
	v_lshl_add_u64 v[128:129], v[130:131], 0, v[226:227]
	global_load_dwordx4 v[140:143], v[128:129], off
	global_load_dwordx4 v[136:139], v[128:129], off offset:256
	v_lshl_add_u64 v[224:225], v[248:249], 0, s[42:43]
	v_lshl_add_u64 v[128:129], v[130:131], 0, v[224:225]
	s_waitcnt vmcnt(14)
	v_pk_mul_f32 v[212:213], v[134:135], 0.5 op_sel_hi:[1,0]
	v_pk_mul_f32 v[210:211], v[132:133], 0.5 op_sel_hi:[1,0]
	global_load_dwordx4 v[132:135], v[128:129], off
	s_nop 0
	global_load_dwordx4 v[128:131], v[128:129], off offset:256
	s_waitcnt vmcnt(15)
	v_lshlrev_b32_e32 v250, 16, v244
	v_and_b32_e32 v251, 0xffff0000, v244
	v_lshlrev_b32_e32 v244, 16, v245
	v_and_b32_e32 v245, 0xffff0000, v245
	v_lshlrev_b32_e32 v252, 16, v246
	v_and_b32_e32 v253, 0xffff0000, v246
	v_lshlrev_b32_e32 v246, 16, v247
	v_and_b32_e32 v247, 0xffff0000, v247
	v_pk_fma_f32 v[124:125], v[124:125], v[218:219], v[250:251]
	v_pk_fma_f32 v[126:127], v[126:127], v[220:221], v[244:245]
	v_pk_fma_f32 v[244:245], v[122:123], v[216:217], v[246:247]
	v_pk_fma_f32 v[122:123], v[120:121], v[214:215], v[252:253]
	v_cvt_pk_bf16_f32 v120, v124, v125
	v_lshl_add_u64 v[124:125], s[24:25], 0, v[248:249]
	v_cvt_pk_bf16_f32 v121, v126, v127
	v_cvt_pk_bf16_f32 v122, v122, v123
	v_cvt_pk_bf16_f32 v123, v244, v245
	v_lshl_add_u64 v[124:125], v[124:125], 0, v[222:223]
	global_store_dwordx4 v[124:125], v[120:123], off sc1
	s_waitcnt vmcnt(15)
	v_lshlrev_b32_e32 v126, 16, v186
	v_and_b32_e32 v127, 0xffff0000, v186
	v_lshlrev_b32_e32 v120, 16, v184
	v_and_b32_e32 v121, 0xffff0000, v184
	v_lshlrev_b32_e32 v122, 16, v185
	v_and_b32_e32 v123, 0xffff0000, v185
	v_lshlrev_b32_e32 v184, 16, v187
	v_and_b32_e32 v185, 0xffff0000, v187
	v_pk_fma_f32 v[118:119], v[118:119], v[212:213], v[122:123]
	v_pk_fma_f32 v[116:117], v[116:117], v[210:211], v[120:121]
	v_pk_fma_f32 v[120:121], v[110:111], v[208:209], v[184:185]
	v_pk_fma_f32 v[110:111], v[108:109], v[206:207], v[126:127]
	v_cvt_pk_bf16_f32 v108, v116, v117
	v_cvt_pk_bf16_f32 v109, v118, v119
	v_cvt_pk_bf16_f32 v110, v110, v111
	v_cvt_pk_bf16_f32 v111, v120, v121
	global_store_dwordx4 v[124:125], v[108:111], off offset:256 sc1
	s_waitcnt vmcnt(15)
	v_lshlrev_b32_e32 v116, 16, v182
	v_and_b32_e32 v117, 0xffff0000, v182
	v_lshlrev_b32_e32 v108, 16, v180
	v_and_b32_e32 v109, 0xffff0000, v180
	v_lshlrev_b32_e32 v110, 16, v181
	v_and_b32_e32 v111, 0xffff0000, v181
	v_lshlrev_b32_e32 v118, 16, v183
	v_and_b32_e32 v119, 0xffff0000, v183
	v_pk_fma_f32 v[108:109], v[112:113], v[218:219], v[108:109]
	v_pk_fma_f32 v[110:111], v[114:115], v[220:221], v[110:111]
	v_pk_fma_f32 v[112:113], v[106:107], v[216:217], v[118:119]
	v_pk_fma_f32 v[106:107], v[104:105], v[214:215], v[116:117]
	v_cvt_pk_bf16_f32 v104, v108, v109
	v_lshl_add_u64 v[108:109], s[24:25], 0, v[236:237]
	v_cvt_pk_bf16_f32 v105, v110, v111
	v_cvt_pk_bf16_f32 v106, v106, v107
	v_cvt_pk_bf16_f32 v107, v112, v113
	v_lshl_add_u64 v[108:109], v[108:109], 0, v[222:223]
	global_store_dwordx4 v[108:109], v[104:107], off sc1
	s_waitcnt vmcnt(15)
; __device__ __forceinline__ unsigned cvt_pk_bf16(float lo, float hi) { f32x2c_t v = {lo, hi}; bf16x2c_t b = __builtin_convertvector(v, bf16x2c_t); return __builtin_bit_cast(unsigned, b); }
; __device__ __forceinline__ f32x4 bf4_lo(u32x4 w) { return (f32x4){__uint_as_float(w.x << 16), __uint_as_float(w.x & 0xffff0000u), __uint_as_float(w.y << 16), __uint_as_float(w.y & 0xffff0000u)}; }
; __device__ __forceinline__ f32x4 bf4_hi(u32x4 w) { return (f32x4){__uint_as_float(w.z << 16), __uint_as_float(w.z & 0xffff0000u), __uint_as_float(w.w << 16), __uint_as_float(w.w & 0xffff0000u)}; }
;     __device__ __forceinline__ void operator()(const f32x4 (&acc)[2][2][4][2], const Unit& u, int wr, int wc, int fr, int fq) const {
;     ...
;         for (int ai = 0; ai < 2; ++ai)
; #pragma unroll
;             for (int m = 0; m < 4; ++m) { const int row = row0 + ai * HALF + m * 16; const size_t off = (size_t)row * 1024 + col0; float rs = 1.f; if constexpr (MIX) { const float* sp = rs2 + 4 * row + 2; rs = 1.0f / sqrtf((sp[0] + sp[1]) * (1.f / 512.f) + NEPS); }
; #pragma unroll
;                 for (int bj = 0; bj < 2; ++bj) { f32x4 x0, x1;
;                     if constexpr (XF32) { x0 = *(const f32x4*)((const float*)xin + off + bj * HALF); x1 = *(const f32x4*)((const float*)xin + off + bj * HALF + 4); }
;                     else { const u32x4 w = xw[ai][m][bj]; x0 = bf4_lo(w); x1 = bf4_hi(w); }
;                     const f32x4 o0 = x0 + gv[bj][0] * (acc[ai][bj][m][0] * rs), o1 = x1 + gv[bj][1] * (acc[ai][bj][m][1] * rs);
;                     u32x4 w; w.x = cvt_pk_bf16(o0[0], o0[1]); w.y = cvt_pk_bf16(o0[2], o0[3]); w.z = cvt_pk_bf16(o1[0], o1[1]); w.w = cvt_pk_bf16(o1[2], o1[3]);
;                     *(u32x4*)(xout + off + bj * HALF) = w; } }
	v_lshlrev_b32_e32 v110, 16, v178
	v_and_b32_e32 v111, 0xffff0000, v178
	v_lshlrev_b32_e32 v104, 16, v176
	v_and_b32_e32 v105, 0xffff0000, v176
	v_lshlrev_b32_e32 v106, 16, v177
	v_and_b32_e32 v107, 0xffff0000, v177
	v_lshlrev_b32_e32 v112, 16, v179
	v_and_b32_e32 v113, 0xffff0000, v179
	v_pk_fma_f32 v[102:103], v[102:103], v[212:213], v[106:107]
	v_pk_fma_f32 v[100:101], v[100:101], v[210:211], v[104:105]
	v_pk_fma_f32 v[104:105], v[94:95], v[208:209], v[112:113]
	v_pk_fma_f32 v[94:95], v[92:93], v[206:207], v[110:111]
	v_cvt_pk_bf16_f32 v92, v100, v101
	v_cvt_pk_bf16_f32 v93, v102, v103
	v_cvt_pk_bf16_f32 v94, v94, v95
	v_cvt_pk_bf16_f32 v95, v104, v105
	global_store_dwordx4 v[108:109], v[92:95], off offset:256 sc1
	s_waitcnt vmcnt(15)
	v_lshlrev_b32_e32 v100, 16, v174
	v_and_b32_e32 v101, 0xffff0000, v174
	v_lshlrev_b32_e32 v92, 16, v172
	v_and_b32_e32 v93, 0xffff0000, v172
	v_lshlrev_b32_e32 v94, 16, v173
	v_and_b32_e32 v95, 0xffff0000, v173
	v_lshlrev_b32_e32 v102, 16, v175
	v_and_b32_e32 v103, 0xffff0000, v175
	v_pk_fma_f32 v[92:93], v[96:97], v[218:219], v[92:93]
	v_pk_fma_f32 v[94:95], v[98:99], v[220:221], v[94:95]
	v_pk_fma_f32 v[96:97], v[90:91], v[216:217], v[102:103]
	v_pk_fma_f32 v[90:91], v[88:89], v[214:215], v[100:101]
	v_cvt_pk_bf16_f32 v88, v92, v93
	v_lshl_add_u64 v[92:93], s[24:25], 0, v[234:235]
	v_cvt_pk_bf16_f32 v89, v94, v95
	v_cvt_pk_bf16_f32 v90, v90, v91
	v_cvt_pk_bf16_f32 v91, v96, v97
	v_lshl_add_u64 v[92:93], v[92:93], 0, v[222:223]
	global_store_dwordx4 v[92:93], v[88:91], off sc1
	s_waitcnt vmcnt(15)
	v_lshlrev_b32_e32 v94, 16, v170
	v_and_b32_e32 v95, 0xffff0000, v170
	v_lshlrev_b32_e32 v88, 16, v168
	v_and_b32_e32 v89, 0xffff0000, v168
	v_lshlrev_b32_e32 v90, 16, v169
	v_and_b32_e32 v91, 0xffff0000, v169
	v_lshlrev_b32_e32 v96, 16, v171
	v_and_b32_e32 v97, 0xffff0000, v171
	v_pk_fma_f32 v[86:87], v[86:87], v[212:213], v[90:91]
	v_pk_fma_f32 v[84:85], v[84:85], v[210:211], v[88:89]
	v_pk_fma_f32 v[88:89], v[78:79], v[208:209], v[96:97]
	v_pk_fma_f32 v[78:79], v[76:77], v[206:207], v[94:95]
	v_cvt_pk_bf16_f32 v76, v84, v85
	v_cvt_pk_bf16_f32 v77, v86, v87
	v_cvt_pk_bf16_f32 v78, v78, v79
	v_cvt_pk_bf16_f32 v79, v88, v89
	global_store_dwordx4 v[92:93], v[76:79], off offset:256 sc1
	s_waitcnt vmcnt(15)
	v_lshlrev_b32_e32 v84, 16, v166
	v_and_b32_e32 v85, 0xffff0000, v166
	v_lshlrev_b32_e32 v76, 16, v164
	v_and_b32_e32 v77, 0xffff0000, v164
	v_lshlrev_b32_e32 v78, 16, v165
	v_and_b32_e32 v79, 0xffff0000, v165
	v_lshlrev_b32_e32 v86, 16, v167
	v_and_b32_e32 v87, 0xffff0000, v167
	v_pk_fma_f32 v[76:77], v[80:81], v[218:219], v[76:77]
	v_pk_fma_f32 v[78:79], v[82:83], v[220:221], v[78:79]
	v_pk_fma_f32 v[80:81], v[74:75], v[216:217], v[86:87]
	v_pk_fma_f32 v[74:75], v[72:73], v[214:215], v[84:85]
	v_cvt_pk_bf16_f32 v72, v76, v77
	v_lshl_add_u64 v[76:77], s[24:25], 0, v[232:233]
	v_cvt_pk_bf16_f32 v73, v78, v79
	v_cvt_pk_bf16_f32 v74, v74, v75
	v_cvt_pk_bf16_f32 v75, v80, v81
	v_lshl_add_u64 v[76:77], v[76:77], 0, v[222:223]
	global_store_dwordx4 v[76:77], v[72:75], off sc1
	s_waitcnt vmcnt(15)
	v_lshlrev_b32_e32 v78, 16, v162
	v_and_b32_e32 v79, 0xffff0000, v162
	v_lshlrev_b32_e32 v72, 16, v160
	v_and_b32_e32 v73, 0xffff0000, v160
	v_lshlrev_b32_e32 v74, 16, v161
	v_and_b32_e32 v75, 0xffff0000, v161
	v_lshlrev_b32_e32 v80, 16, v163
	v_and_b32_e32 v81, 0xffff0000, v163
	v_pk_fma_f32 v[70:71], v[70:71], v[212:213], v[74:75]
	v_pk_fma_f32 v[68:69], v[68:69], v[210:211], v[72:73]
	v_pk_fma_f32 v[72:73], v[66:67], v[208:209], v[80:81]
	v_pk_fma_f32 v[66:67], v[64:65], v[206:207], v[78:79]
	v_cvt_pk_bf16_f32 v64, v68, v69
	v_cvt_pk_bf16_f32 v65, v70, v71
	v_cvt_pk_bf16_f32 v66, v66, v67
	v_cvt_pk_bf16_f32 v67, v72, v73
	global_store_dwordx4 v[76:77], v[64:67], off offset:256 sc1
	s_waitcnt vmcnt(15)
	v_lshlrev_b32_e32 v68, 16, v158
	v_and_b32_e32 v69, 0xffff0000, v158
	v_lshlrev_b32_e32 v64, 16, v156
	v_and_b32_e32 v65, 0xffff0000, v156
	v_lshlrev_b32_e32 v66, 16, v157
	v_and_b32_e32 v67, 0xffff0000, v157
	v_lshlrev_b32_e32 v70, 16, v159
	v_and_b32_e32 v71, 0xffff0000, v159
	v_pk_fma_f32 v[60:61], v[60:61], v[218:219], v[64:65]
	v_pk_fma_f32 v[62:63], v[62:63], v[220:221], v[66:67]
	v_pk_fma_f32 v[64:65], v[58:59], v[216:217], v[70:71]
	v_pk_fma_f32 v[58:59], v[56:57], v[214:215], v[68:69]
	v_cvt_pk_bf16_f32 v56, v60, v61
	v_lshl_add_u64 v[60:61], s[24:25], 0, v[230:231]
	v_cvt_pk_bf16_f32 v57, v62, v63
	v_cvt_pk_bf16_f32 v58, v58, v59
	v_cvt_pk_bf16_f32 v59, v64, v65
	v_lshl_add_u64 v[60:61], v[60:61], 0, v[222:223]
	global_store_dwordx4 v[60:61], v[56:59], off sc1
	s_waitcnt vmcnt(15)
	v_lshlrev_b32_e32 v62, 16, v154
	v_and_b32_e32 v63, 0xffff0000, v154
	v_lshlrev_b32_e32 v56, 16, v152
	v_and_b32_e32 v57, 0xffff0000, v152
	v_lshlrev_b32_e32 v58, 16, v153
	v_and_b32_e32 v59, 0xffff0000, v153
	v_lshlrev_b32_e32 v64, 16, v155
	v_and_b32_e32 v65, 0xffff0000, v155
	v_pk_fma_f32 v[54:55], v[54:55], v[212:213], v[58:59]
	v_pk_fma_f32 v[52:53], v[52:53], v[210:211], v[56:57]
	v_pk_fma_f32 v[56:57], v[46:47], v[208:209], v[64:65]
	v_pk_fma_f32 v[46:47], v[44:45], v[206:207], v[62:63]
	v_cvt_pk_bf16_f32 v44, v52, v53
	v_cvt_pk_bf16_f32 v45, v54, v55
	v_cvt_pk_bf16_f32 v46, v46, v47
	v_cvt_pk_bf16_f32 v47, v56, v57
	global_store_dwordx4 v[60:61], v[44:47], off offset:256 sc1
	s_waitcnt vmcnt(15)
; __device__ __forceinline__ unsigned cvt_pk_bf16(float lo, float hi) { f32x2c_t v = {lo, hi}; bf16x2c_t b = __builtin_convertvector(v, bf16x2c_t); return __builtin_bit_cast(unsigned, b); }
; __device__ __forceinline__ f32x4 bf4_lo(u32x4 w) { return (f32x4){__uint_as_float(w.x << 16), __uint_as_float(w.x & 0xffff0000u), __uint_as_float(w.y << 16), __uint_as_float(w.y & 0xffff0000u)}; }
; __device__ __forceinline__ f32x4 bf4_hi(u32x4 w) { return (f32x4){__uint_as_float(w.z << 16), __uint_as_float(w.z & 0xffff0000u), __uint_as_float(w.w << 16), __uint_as_float(w.w & 0xffff0000u)}; }
;     __device__ __forceinline__ void operator()(const f32x4 (&acc)[2][2][4][2], const Unit& u, int wr, int wc, int fr, int fq) const {
;     ...
;         for (int ai = 0; ai < 2; ++ai)
; #pragma unroll
;             for (int m = 0; m < 4; ++m) { const int row = row0 + ai * HALF + m * 16; const size_t off = (size_t)row * 1024 + col0; float rs = 1.f; if constexpr (MIX) { const float* sp = rs2 + 4 * row + 2; rs = 1.0f / sqrtf((sp[0] + sp[1]) * (1.f / 512.f) + NEPS); }
; #pragma unroll
;                 for (int bj = 0; bj < 2; ++bj) { f32x4 x0, x1;
;                     if constexpr (XF32) { x0 = *(const f32x4*)((const float*)xin + off + bj * HALF); x1 = *(const f32x4*)((const float*)xin + off + bj * HALF + 4); }
;                     else { const u32x4 w = xw[ai][m][bj]; x0 = bf4_lo(w); x1 = bf4_hi(w); }
;                     const f32x4 o0 = x0 + gv[bj][0] * (acc[ai][bj][m][0] * rs), o1 = x1 + gv[bj][1] * (acc[ai][bj][m][1] * rs);
;                     u32x4 w; w.x = cvt_pk_bf16(o0[0], o0[1]); w.y = cvt_pk_bf16(o0[2], o0[3]); w.z = cvt_pk_bf16(o1[0], o1[1]); w.w = cvt_pk_bf16(o1[2], o1[3]);
;                     *(u32x4*)(xout + off + bj * HALF) = w; } }
	v_lshlrev_b32_e32 v52, 16, v150
	v_and_b32_e32 v53, 0xffff0000, v150
	v_lshlrev_b32_e32 v44, 16, v148
	v_and_b32_e32 v45, 0xffff0000, v148
	v_lshlrev_b32_e32 v46, 16, v149
	v_and_b32_e32 v47, 0xffff0000, v149
	v_lshlrev_b32_e32 v54, 16, v151
	v_and_b32_e32 v55, 0xffff0000, v151
	v_pk_fma_f32 v[44:45], v[48:49], v[218:219], v[44:45]
	v_pk_fma_f32 v[46:47], v[50:51], v[220:221], v[46:47]
	v_pk_fma_f32 v[48:49], v[42:43], v[216:217], v[54:55]
	v_pk_fma_f32 v[42:43], v[40:41], v[214:215], v[52:53]
	v_cvt_pk_bf16_f32 v40, v44, v45
	v_lshl_add_u64 v[44:45], s[24:25], 0, v[228:229]
	v_cvt_pk_bf16_f32 v41, v46, v47
	v_cvt_pk_bf16_f32 v42, v42, v43
	v_cvt_pk_bf16_f32 v43, v48, v49
	v_lshl_add_u64 v[44:45], v[44:45], 0, v[222:223]
	global_store_dwordx4 v[44:45], v[40:43], off sc1
	s_waitcnt vmcnt(15)
	v_lshlrev_b32_e32 v46, 16, v146
	v_and_b32_e32 v47, 0xffff0000, v146
	v_lshlrev_b32_e32 v40, 16, v144
	v_and_b32_e32 v41, 0xffff0000, v144
	v_lshlrev_b32_e32 v42, 16, v145
	v_and_b32_e32 v43, 0xffff0000, v145
	v_lshlrev_b32_e32 v48, 16, v147
	v_and_b32_e32 v49, 0xffff0000, v147
	v_pk_fma_f32 v[38:39], v[38:39], v[212:213], v[42:43]
	v_pk_fma_f32 v[36:37], v[36:37], v[210:211], v[40:41]
	v_pk_fma_f32 v[40:41], v[30:31], v[208:209], v[48:49]
	v_pk_fma_f32 v[30:31], v[28:29], v[206:207], v[46:47]
	v_cvt_pk_bf16_f32 v28, v36, v37
	v_cvt_pk_bf16_f32 v29, v38, v39
	v_cvt_pk_bf16_f32 v30, v30, v31
	v_cvt_pk_bf16_f32 v31, v40, v41
	global_store_dwordx4 v[44:45], v[28:31], off offset:256 sc1
	s_waitcnt vmcnt(15)
	v_lshlrev_b32_e32 v36, 16, v142
	v_and_b32_e32 v37, 0xffff0000, v142
	v_lshlrev_b32_e32 v28, 16, v140
	v_and_b32_e32 v29, 0xffff0000, v140
	v_lshlrev_b32_e32 v30, 16, v141
	v_and_b32_e32 v31, 0xffff0000, v141
	v_lshlrev_b32_e32 v38, 16, v143
	v_and_b32_e32 v39, 0xffff0000, v143
	v_pk_fma_f32 v[28:29], v[32:33], v[218:219], v[28:29]
	v_pk_fma_f32 v[30:31], v[34:35], v[220:221], v[30:31]
	v_pk_fma_f32 v[32:33], v[26:27], v[216:217], v[38:39]
	v_pk_fma_f32 v[26:27], v[24:25], v[214:215], v[36:37]
	v_cvt_pk_bf16_f32 v24, v28, v29
	v_lshl_add_u64 v[28:29], s[24:25], 0, v[226:227]
	v_cvt_pk_bf16_f32 v25, v30, v31
	v_cvt_pk_bf16_f32 v26, v26, v27
	v_cvt_pk_bf16_f32 v27, v32, v33
	v_lshl_add_u64 v[28:29], v[28:29], 0, v[222:223]
	global_store_dwordx4 v[28:29], v[24:27], off sc1
	s_waitcnt vmcnt(15)
	v_lshlrev_b32_e32 v30, 16, v138
	v_and_b32_e32 v31, 0xffff0000, v138
	v_lshlrev_b32_e32 v24, 16, v136
	v_and_b32_e32 v25, 0xffff0000, v136
	v_lshlrev_b32_e32 v26, 16, v137
	v_and_b32_e32 v27, 0xffff0000, v137
	v_lshlrev_b32_e32 v32, 16, v139
	v_and_b32_e32 v33, 0xffff0000, v139
	v_pk_fma_f32 v[22:23], v[22:23], v[212:213], v[26:27]
	v_pk_fma_f32 v[20:21], v[20:21], v[210:211], v[24:25]
	v_pk_fma_f32 v[24:25], v[14:15], v[208:209], v[32:33]
	v_pk_fma_f32 v[14:15], v[12:13], v[206:207], v[30:31]
	v_cvt_pk_bf16_f32 v12, v20, v21
	v_cvt_pk_bf16_f32 v13, v22, v23
	v_cvt_pk_bf16_f32 v14, v14, v15
	v_cvt_pk_bf16_f32 v15, v24, v25
	global_store_dwordx4 v[28:29], v[12:15], off offset:256 sc1
	s_waitcnt vmcnt(15)
	v_lshlrev_b32_e32 v20, 16, v134
	v_and_b32_e32 v21, 0xffff0000, v134
	v_lshlrev_b32_e32 v12, 16, v132
	v_and_b32_e32 v13, 0xffff0000, v132
	v_lshlrev_b32_e32 v14, 16, v133
	v_and_b32_e32 v15, 0xffff0000, v133
	v_lshlrev_b32_e32 v22, 16, v135
	v_and_b32_e32 v23, 0xffff0000, v135
	v_pk_fma_f32 v[12:13], v[16:17], v[218:219], v[12:13]
	v_pk_fma_f32 v[14:15], v[18:19], v[220:221], v[14:15]
	v_pk_fma_f32 v[16:17], v[10:11], v[216:217], v[22:23]
	v_pk_fma_f32 v[10:11], v[8:9], v[214:215], v[20:21]
	v_cvt_pk_bf16_f32 v8, v12, v13
	v_lshl_add_u64 v[12:13], s[24:25], 0, v[224:225]
	v_cvt_pk_bf16_f32 v9, v14, v15
	v_cvt_pk_bf16_f32 v10, v10, v11
	v_cvt_pk_bf16_f32 v11, v16, v17
	v_lshl_add_u64 v[12:13], v[12:13], 0, v[222:223]
	global_store_dwordx4 v[12:13], v[8:11], off sc1
	s_waitcnt vmcnt(15)
	v_lshlrev_b32_e32 v14, 16, v130
	v_and_b32_e32 v15, 0xffff0000, v130
	v_lshlrev_b32_e32 v8, 16, v128
	v_and_b32_e32 v9, 0xffff0000, v128
	v_lshlrev_b32_e32 v10, 16, v129
	v_and_b32_e32 v11, 0xffff0000, v129
	v_lshlrev_b32_e32 v16, 16, v131
	v_and_b32_e32 v17, 0xffff0000, v131
	v_pk_fma_f32 v[6:7], v[6:7], v[212:213], v[10:11]
	v_pk_fma_f32 v[4:5], v[4:5], v[210:211], v[8:9]
	v_pk_fma_f32 v[8:9], v[2:3], v[208:209], v[16:17]
	v_pk_fma_f32 v[2:3], v[0:1], v[206:207], v[14:15]
	v_cvt_pk_bf16_f32 v0, v4, v5
	v_cvt_pk_bf16_f32 v1, v6, v7
	v_cvt_pk_bf16_f32 v2, v2, v3
	v_cvt_pk_bf16_f32 v3, v8, v9
	global_store_dwordx4 v[12:13], v[0:3], off offset:256 sc1
	s_cbranch_vccnz .LBB0_1093
	s_andn2_b64 vcc, exec, s[6:7]
	s_cbranch_vccnz .LBB0_1092
	s_barrier
	s_branch .LBB0_1092
